# attention tile loops: raised wave priority from the first QK MFMA to the last PV MFMA of a tile
# speedup vs baseline: 1.0040x; 1.0040x over previous
; #define LAS __attribute__((address_space(3)))
; DI void attn_compute_sp4(const bf16x8 (&qf)[4], const bf16x8 (&kf)[4], const bf16x8 (&vf)[2][2], int kt, int d00, const float* lut, AttnSt& st, int win, int dmask) {
;     const int s0 = kt * 32;
;     f32x16 sx;
; #pragma unroll
;     for (int i = 0; i < 16; ++i) sx[i] = 0.f;
; #pragma unroll
;     for (int ks = 0; ks < 4; ++ks) sx = MFMA32(kf[ks], qf[ks], sx);
;     const int d0 = d00 - s0, e = d0 & 3;
;     const bool e0 = (e == 0), e1 = (e == 1), e2 = (e == 2);
;     const LAS float* lb = (const LAS float*)lut + (d0 - e - 20);
;     float sv[4]; float mx = NEGF;
; #pragma unroll
;     for (int g = 0; g < 4; ++g) {
;         const float x = e0 ? sx[4 * g] : (e1 ? sx[4 * g + 1] : (e2 ? sx[4 * g + 2] : sx[4 * g + 3]));
;         const int dist = d0 - (16 * (g >> 1) + 4 * (g & 1)) - e;
;         const bool v = ((unsigned)dist <= (unsigned)win) && ((dist & dmask) == 0);
;         const float bias = lb[20 - (16 * (g >> 1) + 4 * (g & 1))];
;         float sc = fmaf(x, SC2, bias);
;         sc = v ? sc : NEGF;
;         sv[g] = sc; mx = fmaxf(mx, sc);
;     }
;     mx = fmaxf(mx, __shfl_xor(mx, 32));
;     const float mnew = fmaxf(st.m, mx);
;     const float msafe = (mnew > -1e29f) ? mnew : 0.f;
;     if (__ballot(mnew > st.m) != 0ull) {
;         const float alpha = __builtin_amdgcn_exp2f(st.m - msafe);
;         st.l *= alpha; st.m = mnew;
; #pragma unroll
;         for (int i = 0; i < 16; ++i) { st.o0[i] *= alpha; st.o1[i] *= alpha; }
;     }
;     float ps = 0.f; float p[16];
; #pragma unroll
;     for (int g = 0; g < 4; ++g) {
;         const float pe = __builtin_amdgcn_exp2f(sv[g] - msafe); ps += pe;
;         p[4 * g] = e0 ? pe : 0.f; p[4 * g + 1] = e1 ? pe : 0.f; p[4 * g + 2] = e2 ? pe : 0.f; p[4 * g + 3] = (e == 3) ? pe : 0.f;
;     }
;     st.l += ps;
;     u32x4 w0, w1;
;     w0.x = pk2(p[0], p[1]); w0.y = pk2(p[2], p[3]); w0.z = pk2(p[4], p[5]); w0.w = pk2(p[6], p[7]);
;     w1.x = pk2(p[8], p[9]); w1.y = pk2(p[10], p[11]); w1.z = pk2(p[12], p[13]); w1.w = pk2(p[14], p[15]);
;     const bf16x8 pf0 = __builtin_bit_cast(bf16x8, w0), pf1 = __builtin_bit_cast(bf16x8, w1);
;     st.o0 = MFMA32(vf[0][0], pf0, st.o0); st.o0 = MFMA32(vf[0][1], pf1, st.o0);
;     st.o1 = MFMA32(vf[1][0], pf0, st.o1); st.o1 = MFMA32(vf[1][1], pf1, st.o1);
; }
.LBB0_285:
	s_andn2_b64 vcc, exec, s[4:5]
	s_mov_b64 s[46:47], -1
	s_cbranch_vccnz .LBB0_289
	s_waitcnt lgkmcnt(0)
	s_setprio 1
	v_mfma_f32_32x32x16_bf16 v[34:49], v[106:109], v[78:81], 0
	ds_read2_b32 v[50:51], v152 offset0:16 offset1:20
	ds_read2_b32 v[60:61], v152 offset1:4
	v_add_u32_e32 v52, v163, v151
	v_add_u32_e32 v53, 0x98, v52
	v_mov_b32_e32 v172, v150
	v_mov_b32_e32 v169, v153
	v_mfma_f32_32x32x16_bf16 v[34:49], v[110:113], v[74:77], v[34:49]
	v_mfma_f32_32x32x16_bf16 v[34:49], v[102:105], v[70:73], v[34:49]
	v_mfma_f32_32x32x16_bf16 v[34:49], v[98:101], v[66:69], v[34:49]
	s_nop 11
	v_cndmask_b32_e64 v54, v37, v36, s[38:39]
	v_cndmask_b32_e64 v56, v41, v40, s[38:39]
	v_cndmask_b32_e64 v57, v45, v44, s[38:39]
	v_cndmask_b32_e64 v58, v49, v48, s[38:39]
	v_cndmask_b32_e64 v54, v54, v35, s[40:41]
	v_cndmask_b32_e64 v56, v56, v39, s[40:41]
	v_cndmask_b32_e64 v57, v57, v43, s[40:41]
	v_cndmask_b32_e64 v58, v58, v47, s[40:41]
	v_cndmask_b32_e64 v54, v54, v34, s[42:43]
	v_cndmask_b32_e64 v56, v56, v38, s[42:43]
	v_cndmask_b32_e64 v57, v57, v42, s[42:43]
	v_cndmask_b32_e64 v58, v58, v46, s[42:43]
	s_waitcnt lgkmcnt(0)
	v_fmamk_f32 v51, v54, 0x3e38aa3b, v51
	v_cmp_gt_u32_e32 vcc, s31, v53
	v_add_u32_e32 v53, 0x94, v52
	s_nop 0
	v_cndmask_b32_e32 v170, v239, v51, vcc
	v_add_u32_e32 v55, 0x88, v52
	v_fmac_f32_e32 v50, 0x3e38aa3b, v56
	v_cmp_gt_u32_e32 vcc, s31, v53
	s_nop 1
	v_cndmask_b32_e32 v171, v239, v50, vcc
	v_max3_f32 v53, v170, s30, v171
	v_fmamk_f32 v61, v57, 0x3e38aa3b, v61
	v_cmp_gt_u32_e32 vcc, s31, v55
	s_nop 1
	v_cndmask_b32_e32 v173, v239, v61, vcc
	v_add_u32_e32 v35, 0x84, v52
	v_fmac_f32_e32 v60, 0x3e38aa3b, v58
	v_cmp_gt_u32_e32 vcc, s31, v35
	s_nop 1
	v_cndmask_b32_e32 v174, v239, v60, vcc
	v_max3_f32 v34, v53, v173, v174
	v_mov_b32_e32 v35, v34
	s_nop 1
	v_permlane32_swap_b32_e32 v35, v34
	v_mov_b64_e32 v[64:65], v[32:33]
	v_mov_b64_e32 v[62:63], v[30:31]
	v_mov_b64_e32 v[60:61], v[28:29]
	v_mov_b64_e32 v[58:59], v[26:27]
	s_waitcnt lgkmcnt(0)
	v_max3_f32 v176, v153, v34, v35
	v_cmp_lt_f32_e32 vcc, s12, v176
	v_mov_b64_e32 v[48:49], v[16:17]
	v_mov_b64_e32 v[56:57], v[24:25]
	v_cndmask_b32_e32 v175, 0, v176, vcc
	v_cmp_gt_f32_e32 vcc, v176, v153
	v_mov_b64_e32 v[54:55], v[22:23]
	v_mov_b64_e32 v[52:53], v[20:21]
	v_mov_b64_e32 v[50:51], v[18:19]
	v_mov_b64_e32 v[46:47], v[14:15]
	v_mov_b64_e32 v[44:45], v[12:13]
	v_mov_b64_e32 v[42:43], v[10:11]
	v_mov_b64_e32 v[40:41], v[8:9]
	v_mov_b64_e32 v[38:39], v[6:7]
	v_mov_b64_e32 v[36:37], v[4:5]
	v_mov_b64_e32 v[34:35], v[2:3]
	s_cbranch_vccz .LBB0_288
	v_sub_f32_e32 v34, v153, v175
	v_exp_f32_e32 v50, v34
	v_mov_b32_e32 v169, v176
	v_mul_f32_e32 v172, v150, v50
	v_pk_mul_f32 v[48:49], v[16:17], v[50:51] op_sel_hi:[1,0]
	v_pk_mul_f32 v[46:47], v[14:15], v[50:51] op_sel_hi:[1,0]
	v_pk_mul_f32 v[44:45], v[12:13], v[50:51] op_sel_hi:[1,0]
	v_pk_mul_f32 v[42:43], v[10:11], v[50:51] op_sel_hi:[1,0]
	v_pk_mul_f32 v[40:41], v[8:9], v[50:51] op_sel_hi:[1,0]
	v_pk_mul_f32 v[38:39], v[6:7], v[50:51] op_sel_hi:[1,0]
	v_pk_mul_f32 v[36:37], v[4:5], v[50:51] op_sel_hi:[1,0]
	v_pk_mul_f32 v[34:35], v[2:3], v[50:51] op_sel_hi:[1,0]
	v_pk_mul_f32 v[64:65], v[32:33], v[50:51] op_sel_hi:[1,0]
	v_pk_mul_f32 v[62:63], v[30:31], v[50:51] op_sel_hi:[1,0]
	v_pk_mul_f32 v[60:61], v[28:29], v[50:51] op_sel_hi:[1,0]
	v_pk_mul_f32 v[58:59], v[26:27], v[50:51] op_sel_hi:[1,0]
	v_pk_mul_f32 v[56:57], v[24:25], v[50:51] op_sel_hi:[1,0]
	v_pk_mul_f32 v[54:55], v[22:23], v[50:51] op_sel_hi:[1,0]
	v_pk_mul_f32 v[52:53], v[20:21], v[50:51] op_sel_hi:[1,0]
	v_pk_mul_f32 v[50:51], v[18:19], v[50:51] op_sel_hi:[1,0]
.LBB0_288:
	v_sub_f32_e32 v170, v170, v175
	v_sub_f32_e32 v171, v171, v175
	v_exp_f32_e32 v170, v170
	v_exp_f32_e32 v171, v171
	v_sub_f32_e32 v174, v174, v175
	v_sub_f32_e32 v173, v173, v175
	v_cndmask_b32_e64 v176, 0, v170, s[42:43]
	v_cndmask_b32_e64 v177, 0, v170, s[40:41]
	v_cndmask_b32_e64 v178, 0, v170, s[38:39]
	v_cndmask_b32_e64 v179, 0, v170, s[44:45]
	v_cndmask_b32_e64 v180, 0, v171, s[42:43]
	v_cndmask_b32_e64 v181, 0, v171, s[40:41]
	v_cndmask_b32_e64 v182, 0, v171, s[38:39]
	v_cndmask_b32_e64 v183, 0, v171, s[44:45]
	v_exp_f32_e32 v185, v174
	v_cvt_pk_bf16_f32 v174, v176, v177
	v_cvt_pk_bf16_f32 v175, v178, v179
	v_cvt_pk_bf16_f32 v176, v180, v181
	v_cvt_pk_bf16_f32 v177, v182, v183
	v_exp_f32_e32 v173, v173
	v_cndmask_b32_e64 v189, 0, v185, s[42:43]
	v_mfma_f32_32x32x16_bf16 v[34:49], v[94:97], v[174:177], v[34:49]
	v_cndmask_b32_e64 v180, 0, v185, s[40:41]
	v_cndmask_b32_e64 v184, 0, v173, s[42:43]
	v_cndmask_b32_e64 v186, 0, v173, s[40:41]
	v_cndmask_b32_e64 v187, 0, v173, s[38:39]
	v_cndmask_b32_e64 v188, 0, v173, s[44:45]
	v_cndmask_b32_e64 v181, 0, v185, s[38:39]
	v_cndmask_b32_e64 v182, 0, v185, s[44:45]
	v_mfma_f32_32x32x16_bf16 v[50:65], v[86:89], v[174:177], v[50:65]
	v_cvt_pk_bf16_f32 v178, v184, v186
	v_cvt_pk_bf16_f32 v179, v187, v188
	v_cvt_pk_bf16_f32 v180, v189, v180
	v_cvt_pk_bf16_f32 v181, v181, v182
	v_add_f32_e32 v170, 0, v170
	v_add_f32_e32 v170, v171, v170
	v_add_f32_e32 v170, v173, v170
	v_mfma_f32_32x32x16_bf16 v[34:49], v[90:93], v[178:181], v[34:49]
	v_add_f32_e32 v170, v185, v170
	v_add_f32_e32 v170, v170, v172
	v_mfma_f32_32x32x16_bf16 v[50:65], v[82:85], v[178:181], v[50:65]
	s_setprio 0
	s_branch .LBB0_294
; #define LAS __attribute__((address_space(3)))
; #define MFMA32(a, b, c) __builtin_amdgcn_mfma_f32_32x32x16_bf16((a), (b), (c), 0, 0, 0)
; template <int MODE, bool UNI>
; DI void attn_compute(const bf16x8 (&qf)[4], const bf16x8 (&kf)[4], const bf16x8 (&vf)[2][2], int kt, int d00, const float* lut, float ubias, AttnSt& st,
;                      unsigned W, int win, int dmask, bool lane_sel) {
;     const int s0 = kt * 32;
;     const int d0 = d00 - s0;
;     const LAS float* lb = (const LAS float*)lut + ((MODE == 4) ? 16 * (d0 - 23) : (d0 - 23));
;     float bia[16];
;     if (!UNI) {
; #pragma unroll
;         for (int i = 0; i < 16; ++i) { const int ci = 16 * (i >> 3) + (i & 7); bia[i] = (MODE == 4) ? lb[16 * (23 - ci)] : lb[23 - ci]; }
;     }
;     f32x16 sx;
; #pragma unroll
;     for (int i = 0; i < 16; ++i) sx[i] = 0.f;
; #pragma unroll
;     for (int ks = 0; ks < 4; ++ks) sx = MFMA32(kf[ks], qf[ks], sx);
;     asm volatile("s_waitcnt lgkmcnt(0)" ::: "memory");
;     float sv[16]; float mx = NEGF;
; #pragma unroll
;     for (int i = 0; i < 16; ++i) {
;         const int ci = 16 * (i >> 3) + (i & 7);
;         const int dist = d0 - ci;
;         bool v;
;         if (MODE == 0) v = ((W >> ci) & 1u) != 0u;
;         else if (MODE == 1) v = ((unsigned)dist <= (unsigned)win) && ((dist & dmask) == 0);
;         else if (MODE == 2) v = lane_sel;
;         else v = dist >= 0;
;         const float bias = UNI ? ubias : bia[i];
;         float s = fmaf(sx[i], SC2, bias);
;         if (MODE == 0) { const unsigned t = (unsigned)__builtin_amdgcn_sbfe((int)W, ci, 1);
;             s = __uint_as_float((__float_as_uint(s) & t) | (__float_as_uint(NEGF) & ~t)); }
;         else s = v ? s : NEGF;
;         sv[i] = s; mx = fmaxf(mx, s);
;     }
;     mx = fmaxf(mx, __shfl_xor(mx, 32));
;     const float mnew = fmaxf(st.m, mx);
;     const float msafe = (mnew > -1e29f) ? mnew : 0.f;
;     if (__ballot(mnew > st.m) != 0ull) {
;         const float alpha = __builtin_amdgcn_exp2f(st.m - msafe);
;         st.l *= alpha; st.m = mnew;
; #pragma unroll
;         for (int i = 0; i < 16; ++i) { st.o0[i] *= alpha; st.o1[i] *= alpha; }
;     }
.LBB0_289:
	s_and_b64 vcc, exec, s[46:47]
	s_cbranch_vccz .LBB0_294
	s_waitcnt lgkmcnt(0)
	s_setprio 1
	v_mfma_f32_32x32x16_bf16 v[34:49], v[106:109], v[78:81], 0
	ds_read2_b32 v[50:51], v0 offset0:22 offset1:23
	ds_read2_b32 v[52:53], v0 offset0:20 offset1:21
	ds_read2_b32 v[54:55], v0 offset0:18 offset1:19
	ds_read2_b32 v[56:57], v0 offset0:16 offset1:17
	v_add_u32_e32 v106, 0x98, v151
	v_cmp_gt_u32_e32 vcc, s95, v106
	v_add_u32_e32 v107, 18, v151
	ds_read2_b32 v[58:59], v0 offset0:6 offset1:7
	ds_read2_b32 v[60:61], v0 offset0:4 offset1:5
	ds_read2_b32 v[62:63], v0 offset0:2 offset1:3
	ds_read2_b32 v[64:65], v0 offset1:1
	v_mfma_f32_32x32x16_bf16 v[34:49], v[110:113], v[74:77], v[34:49]
	v_mfma_f32_32x32x16_bf16 v[34:49], v[102:105], v[70:73], v[34:49]
	v_add_u32_e32 v102, 22, v151
	v_add_u32_e32 v103, 21, v151
	v_add_u32_e32 v104, 20, v151
	v_add_u32_e32 v105, 19, v151
	v_mfma_f32_32x32x16_bf16 v[34:49], v[98:101], v[66:69], v[34:49]
	s_waitcnt lgkmcnt(0)
	s_nop 10
	v_fmamk_f32 v34, v34, 0x3e38aa3b, v51
	v_fmac_f32_e32 v50, 0x3e38aa3b, v35
	v_cndmask_b32_e32 v35, v239, v34, vcc
	v_cmp_lt_u32_e32 vcc, s13, v102
	v_fmamk_f32 v51, v36, 0x3e38aa3b, v53
	v_fmac_f32_e32 v52, 0x3e38aa3b, v37
	v_cndmask_b32_e32 v36, v239, v50, vcc
	v_cmp_lt_u32_e32 vcc, s13, v103
	v_fmamk_f32 v38, v38, 0x3e38aa3b, v55
	v_fmac_f32_e32 v54, 0x3e38aa3b, v39
	v_cndmask_b32_e32 v37, v239, v51, vcc
	v_cmp_lt_u32_e32 vcc, s13, v104
	v_add_u32_e32 v51, 17, v151
	v_fmamk_f32 v40, v40, 0x3e38aa3b, v57
	v_cndmask_b32_e32 v34, v239, v52, vcc
	v_cmp_lt_u32_e32 vcc, s13, v105
	v_fmac_f32_e32 v56, 0x3e38aa3b, v41
	v_fmamk_f32 v42, v42, 0x3e38aa3b, v59
	v_cndmask_b32_e32 v39, v239, v38, vcc
	v_cmp_lt_u32_e32 vcc, s13, v107
	v_max3_f32 v38, v35, s30, v36
	v_fmac_f32_e32 v58, 0x3e38aa3b, v43
	v_cndmask_b32_e32 v50, v239, v54, vcc
	v_cmp_lt_u32_e32 vcc, s13, v51
	v_max3_f32 v38, v38, v37, v34
	v_fmamk_f32 v44, v44, 0x3e38aa3b, v61
	v_cndmask_b32_e32 v51, v239, v40, vcc
	v_add_u32_e32 v40, 16, v151
	v_cmp_lt_u32_e32 vcc, s13, v40
	v_add_u32_e32 v40, 7, v151
	v_max3_f32 v38, v38, v39, v50
	v_cndmask_b32_e32 v41, v239, v56, vcc
	v_cmp_lt_u32_e32 vcc, s13, v40
	v_add_u32_e32 v40, 6, v151
	v_fmac_f32_e32 v60, 0x3e38aa3b, v45
	v_cndmask_b32_e32 v42, v239, v42, vcc
	v_cmp_lt_u32_e32 vcc, s13, v40
	v_add_u32_e32 v40, 5, v151
	v_max3_f32 v38, v38, v51, v41
	v_cndmask_b32_e32 v43, v239, v58, vcc
	v_cmp_lt_u32_e32 vcc, s13, v40
	v_add_u32_e32 v40, 4, v151
	v_fmamk_f32 v46, v46, 0x3e38aa3b, v63
	v_cndmask_b32_e32 v44, v239, v44, vcc
	v_cmp_lt_u32_e32 vcc, s13, v40
	v_add_u32_e32 v40, 3, v151
	v_max3_f32 v38, v38, v42, v43
	v_cndmask_b32_e32 v45, v239, v60, vcc
	v_cmp_lt_u32_e32 vcc, s13, v40
	v_add_u32_e32 v40, 2, v151
	v_fmac_f32_e32 v62, 0x3e38aa3b, v47
	v_cndmask_b32_e32 v46, v239, v46, vcc
	v_cmp_lt_u32_e32 vcc, s13, v40
	v_max3_f32 v38, v38, v44, v45
	v_fmamk_f32 v48, v48, 0x3e38aa3b, v65
	v_cndmask_b32_e32 v47, v239, v62, vcc
	v_max3_f32 v40, v38, v46, v47
	v_add_u32_e32 v38, 1, v151
	v_cmp_lt_u32_e32 vcc, s13, v38
	v_fmac_f32_e32 v64, 0x3e38aa3b, v49
	s_nop 0
	v_cndmask_b32_e32 v48, v239, v48, vcc
	v_cmp_lt_u32_e32 vcc, s13, v151
	s_nop 1
	v_cndmask_b32_e32 v38, v239, v64, vcc
	v_max3_f32 v40, v40, v48, v38
	v_mov_b32_e32 v49, v40
	s_nop 1
	v_permlane32_swap_b32_e32 v49, v40
	s_waitcnt lgkmcnt(0)
	v_max3_f32 v169, v153, v40, v49
	v_cmp_lt_f32_e32 vcc, s12, v169
	s_nop 1
	v_cndmask_b32_e32 v40, 0, v169, vcc
	v_cmp_gt_f32_e32 vcc, v169, v153
	s_cbranch_vccz .LBB0_292
	v_sub_f32_e32 v49, v153, v40
	v_exp_f32_e32 v52, v49
	s_nop 0
	v_mul_f32_e32 v150, v150, v52
	v_pk_mul_f32 v[16:17], v[16:17], v[52:53] op_sel_hi:[1,0]
	v_pk_mul_f32 v[14:15], v[14:15], v[52:53] op_sel_hi:[1,0]
	v_pk_mul_f32 v[12:13], v[12:13], v[52:53] op_sel_hi:[1,0]
	v_pk_mul_f32 v[10:11], v[10:11], v[52:53] op_sel_hi:[1,0]
	v_pk_mul_f32 v[8:9], v[8:9], v[52:53] op_sel_hi:[1,0]
	v_pk_mul_f32 v[6:7], v[6:7], v[52:53] op_sel_hi:[1,0]
	v_pk_mul_f32 v[4:5], v[4:5], v[52:53] op_sel_hi:[1,0]
	v_pk_mul_f32 v[2:3], v[2:3], v[52:53] op_sel_hi:[1,0]
	v_pk_mul_f32 v[32:33], v[32:33], v[52:53] op_sel_hi:[1,0]
	v_pk_mul_f32 v[30:31], v[30:31], v[52:53] op_sel_hi:[1,0]
	v_pk_mul_f32 v[28:29], v[28:29], v[52:53] op_sel_hi:[1,0]
	v_pk_mul_f32 v[26:27], v[26:27], v[52:53] op_sel_hi:[1,0]
	v_pk_mul_f32 v[24:25], v[24:25], v[52:53] op_sel_hi:[1,0]
	v_pk_mul_f32 v[22:23], v[22:23], v[52:53] op_sel_hi:[1,0]
	v_pk_mul_f32 v[20:21], v[20:21], v[52:53] op_sel_hi:[1,0]
	v_pk_mul_f32 v[18:19], v[18:19], v[52:53] op_sel_hi:[1,0]
	s_branch .LBB0_293

; DI unsigned pk2(float lo, float hi) { f32x2 v = {lo, hi}; bf2_t b = __builtin_convertvector(v, bf2_t); return __builtin_bit_cast(unsigned, b); }
; #define MFMA32(a, b, c) __builtin_amdgcn_mfma_f32_32x32x16_bf16((a), (b), (c), 0, 0, 0)
; template <int MODE, bool UNI>
; DI void attn_compute(const bf16x8 (&qf)[4], const bf16x8 (&kf)[4], const bf16x8 (&vf)[2][2], int kt, int d00, const float* lut, float ubias, AttnSt& st,
;                      unsigned W, int win, int dmask, bool lane_sel) {
;     ...
;     float ps = 0.f; float p[16];
; #pragma unroll
;     for (int i = 0; i < 16; ++i) { const float e = __builtin_amdgcn_exp2f(sv[i] - msafe); p[i] = e; ps += e; }
;     st.l += ps;
;     u32x4 w0, w1;
;     w0.x = pk2(p[0], p[1]); w0.y = pk2(p[2], p[3]); w0.z = pk2(p[4], p[5]); w0.w = pk2(p[6], p[7]);
;     w1.x = pk2(p[8], p[9]); w1.y = pk2(p[10], p[11]); w1.z = pk2(p[12], p[13]); w1.w = pk2(p[14], p[15]);
;     const bf16x8 pf0 = __builtin_bit_cast(bf16x8, w0), pf1 = __builtin_bit_cast(bf16x8, w1);
;     st.o0 = MFMA32(vf[0][0], pf0, st.o0); st.o0 = MFMA32(vf[0][1], pf1, st.o0);
;     st.o1 = MFMA32(vf[1][0], pf0, st.o1); st.o1 = MFMA32(vf[1][1], pf1, st.o1);
.LBB0_293:
	v_sub_f32_e32 v34, v34, v40
	v_exp_f32_e32 v52, v34
	v_sub_f32_e32 v34, v39, v40
	v_exp_f32_e32 v53, v34
	v_sub_f32_e32 v34, v50, v40
	v_exp_f32_e32 v50, v34
	v_sub_f32_e32 v34, v51, v40
	v_sub_f32_e32 v35, v35, v40
	v_exp_f32_e32 v51, v34
	v_sub_f32_e32 v34, v41, v40
	v_exp_f32_e32 v35, v35
	v_sub_f32_e32 v36, v36, v40
	v_exp_f32_e32 v54, v34
	v_sub_f32_e32 v34, v42, v40
	v_exp_f32_e32 v36, v36
	v_sub_f32_e32 v37, v37, v40
	v_exp_f32_e32 v42, v34
	v_sub_f32_e32 v34, v43, v40
	v_exp_f32_e32 v37, v37
	v_exp_f32_e32 v43, v34
	v_sub_f32_e32 v34, v44, v40
	v_exp_f32_e32 v44, v34
	v_sub_f32_e32 v34, v45, v40
	v_add_f32_e32 v49, 0, v35
	v_exp_f32_e32 v45, v34
	v_sub_f32_e32 v34, v46, v40
	v_add_f32_e32 v49, v36, v49
	v_exp_f32_e32 v46, v34
	v_sub_f32_e32 v34, v47, v40
	v_add_f32_e32 v49, v37, v49
	v_exp_f32_e32 v47, v34
	v_cvt_pk_bf16_f32 v34, v35, v36
	v_cvt_pk_bf16_f32 v35, v37, v52
	v_cvt_pk_bf16_f32 v36, v53, v50
	v_cvt_pk_bf16_f32 v37, v51, v54
	v_sub_f32_e32 v39, v48, v40
	v_sub_f32_e32 v38, v38, v40
	v_mfma_f32_32x32x16_bf16 v[2:17], v[94:97], v[34:37], v[2:17]
	v_exp_f32_e32 v48, v39
	v_exp_f32_e32 v55, v38
	v_add_f32_e32 v49, v52, v49
	v_add_f32_e32 v49, v53, v49
	v_add_f32_e32 v49, v50, v49
	v_add_f32_e32 v49, v51, v49
	v_cvt_pk_bf16_f32 v38, v42, v43
	v_mfma_f32_32x32x16_bf16 v[18:33], v[86:89], v[34:37], v[18:33]
	v_cvt_pk_bf16_f32 v39, v44, v45
	v_cvt_pk_bf16_f32 v40, v46, v47
	v_cvt_pk_bf16_f32 v41, v48, v55
	v_add_f32_e32 v49, v54, v49
	v_add_f32_e32 v42, v42, v49
	v_add_f32_e32 v42, v43, v42
	v_add_f32_e32 v34, v44, v42
	v_mfma_f32_32x32x16_bf16 v[2:17], v[90:93], v[38:41], v[2:17]
	v_add_f32_e32 v34, v45, v34
	v_add_f32_e32 v34, v46, v34
	v_add_f32_e32 v34, v47, v34
	v_add_f32_e32 v34, v48, v34
	v_add_f32_e32 v34, v55, v34
	v_add_f32_e32 v170, v34, v150
	v_mfma_f32_32x32x16_bf16 v[18:33], v[82:85], v[38:41], v[18:33]
	s_setprio 0
	s_nop 4
	v_mov_b64_e32 v[48:49], v[16:17]
	v_mov_b64_e32 v[46:47], v[14:15]
	v_mov_b64_e32 v[44:45], v[12:13]
	v_mov_b64_e32 v[42:43], v[10:11]
	v_mov_b64_e32 v[40:41], v[8:9]
	v_mov_b64_e32 v[38:39], v[6:7]
	v_mov_b64_e32 v[36:37], v[4:5]
	v_mov_b64_e32 v[64:65], v[32:33]
	v_mov_b64_e32 v[62:63], v[30:31]
	v_mov_b64_e32 v[60:61], v[28:29]
	v_mov_b64_e32 v[58:59], v[26:27]
	v_mov_b64_e32 v[56:57], v[24:25]
	v_mov_b64_e32 v[54:55], v[22:23]
	v_mov_b64_e32 v[52:53], v[20:21]
	v_mov_b64_e32 v[50:51], v[18:19]
	v_mov_b64_e32 v[34:35], v[2:3]

; #define LAS __attribute__((address_space(3)))
; DI void attn_compute_sp4(const bf16x8 (&qf)[4], const bf16x8 (&kf)[4], const bf16x8 (&vf)[2][2], int kt, int d00, const float* lut, AttnSt& st, int win, int dmask) {
;     const int s0 = kt * 32;
;     f32x16 sx;
; #pragma unroll
;     for (int i = 0; i < 16; ++i) sx[i] = 0.f;
; #pragma unroll
;     for (int ks = 0; ks < 4; ++ks) sx = MFMA32(kf[ks], qf[ks], sx);
;     const int d0 = d00 - s0, e = d0 & 3;
;     const bool e0 = (e == 0), e1 = (e == 1), e2 = (e == 2);
;     const LAS float* lb = (const LAS float*)lut + (d0 - e - 20);
;     float sv[4]; float mx = NEGF;
; #pragma unroll
;     for (int g = 0; g < 4; ++g) {
;         const float x = e0 ? sx[4 * g] : (e1 ? sx[4 * g + 1] : (e2 ? sx[4 * g + 2] : sx[4 * g + 3]));
;         const int dist = d0 - (16 * (g >> 1) + 4 * (g & 1)) - e;
;         const bool v = ((unsigned)dist <= (unsigned)win) && ((dist & dmask) == 0);
;         const float bias = lb[20 - (16 * (g >> 1) + 4 * (g & 1))];
;         float sc = fmaf(x, SC2, bias);
;         sc = v ? sc : NEGF;
;         sv[g] = sc; mx = fmaxf(mx, sc);
;     }
;     mx = fmaxf(mx, __shfl_xor(mx, 32));
;     const float mnew = fmaxf(st.m, mx);
;     const float msafe = (mnew > -1e29f) ? mnew : 0.f;
;     if (__ballot(mnew > st.m) != 0ull) {
;         const float alpha = __builtin_amdgcn_exp2f(st.m - msafe);
;         st.l *= alpha; st.m = mnew;
; #pragma unroll
;         for (int i = 0; i < 16; ++i) { st.o0[i] *= alpha; st.o1[i] *= alpha; }
;     }
;     float ps = 0.f; float p[16];
; #pragma unroll
;     for (int g = 0; g < 4; ++g) {
;         const float pe = __builtin_amdgcn_exp2f(sv[g] - msafe); ps += pe;
;         p[4 * g] = e0 ? pe : 0.f; p[4 * g + 1] = e1 ? pe : 0.f; p[4 * g + 2] = e2 ? pe : 0.f; p[4 * g + 3] = (e == 3) ? pe : 0.f;
;     }
;     st.l += ps;
;     u32x4 w0, w1;
;     w0.x = pk2(p[0], p[1]); w0.y = pk2(p[2], p[3]); w0.z = pk2(p[4], p[5]); w0.w = pk2(p[6], p[7]);
;     w1.x = pk2(p[8], p[9]); w1.y = pk2(p[10], p[11]); w1.z = pk2(p[12], p[13]); w1.w = pk2(p[14], p[15]);
;     const bf16x8 pf0 = __builtin_bit_cast(bf16x8, w0), pf1 = __builtin_bit_cast(bf16x8, w1);
;     st.o0 = MFMA32(vf[0][0], pf0, st.o0); st.o0 = MFMA32(vf[0][1], pf1, st.o0);
;     st.o1 = MFMA32(vf[1][0], pf0, st.o1); st.o1 = MFMA32(vf[1][1], pf1, st.o1);
; }
.LBB0_304:
	s_andn2_b64 vcc, exec, s[4:5]
	s_mov_b64 s[46:47], -1
	s_cbranch_vccnz .LBB0_308
	s_waitcnt lgkmcnt(0)
	s_setprio 1
	v_mfma_f32_32x32x16_bf16 v[2:17], v[106:109], v[78:81], 0
	ds_read2_b32 v[50:51], v171 offset0:16 offset1:20
	ds_read2_b32 v[60:61], v171 offset1:4
	v_add_u32_e32 v52, v163, v170
	v_add_u32_e32 v53, 0x98, v52
	v_mov_b32_e32 v176, v149
	v_mov_b32_e32 v173, v172
	v_mfma_f32_32x32x16_bf16 v[2:17], v[110:113], v[74:77], v[2:17]
	v_mfma_f32_32x32x16_bf16 v[2:17], v[102:105], v[70:73], v[2:17]
	v_mfma_f32_32x32x16_bf16 v[2:17], v[98:101], v[66:69], v[2:17]
	s_nop 11
	v_cndmask_b32_e64 v54, v5, v4, s[38:39]
	v_cndmask_b32_e64 v56, v9, v8, s[38:39]
	v_cndmask_b32_e64 v57, v13, v12, s[38:39]
	v_cndmask_b32_e64 v58, v17, v16, s[38:39]
	v_cndmask_b32_e64 v54, v54, v3, s[40:41]
	v_cndmask_b32_e64 v56, v56, v7, s[40:41]
	v_cndmask_b32_e64 v57, v57, v11, s[40:41]
	v_cndmask_b32_e64 v58, v58, v15, s[40:41]
	v_cndmask_b32_e64 v54, v54, v2, s[42:43]
	v_cndmask_b32_e64 v56, v56, v6, s[42:43]
	v_cndmask_b32_e64 v57, v57, v10, s[42:43]
	v_cndmask_b32_e64 v58, v58, v14, s[42:43]
	s_waitcnt lgkmcnt(0)
	v_fmamk_f32 v51, v54, 0x3e38aa3b, v51
	v_cmp_gt_u32_e32 vcc, s31, v53
	v_add_u32_e32 v53, 0x94, v52
	s_nop 0
	v_cndmask_b32_e32 v174, v239, v51, vcc
	v_add_u32_e32 v55, 0x88, v52
	v_fmac_f32_e32 v50, 0x3e38aa3b, v56
	v_cmp_gt_u32_e32 vcc, s31, v53
	s_nop 1
	v_cndmask_b32_e32 v175, v239, v50, vcc
	v_max3_f32 v53, v174, s30, v175
	v_fmamk_f32 v61, v57, 0x3e38aa3b, v61
	v_cmp_gt_u32_e32 vcc, s31, v55
	s_nop 1
	v_cndmask_b32_e32 v177, v239, v61, vcc
	v_add_u32_e32 v3, 0x84, v52
	v_fmac_f32_e32 v60, 0x3e38aa3b, v58
	v_cmp_gt_u32_e32 vcc, s31, v3
	s_nop 1
	v_cndmask_b32_e32 v178, v239, v60, vcc
	v_max3_f32 v2, v53, v177, v178
	v_mov_b32_e32 v3, v2
	s_nop 1
	v_permlane32_swap_b32_e32 v3, v2
	v_mov_b64_e32 v[64:65], v[48:49]
	v_mov_b64_e32 v[62:63], v[46:47]
	v_mov_b64_e32 v[60:61], v[44:45]
	v_mov_b64_e32 v[58:59], v[42:43]
	s_waitcnt lgkmcnt(0)
	v_max3_f32 v180, v172, v2, v3
	v_cmp_lt_f32_e32 vcc, s12, v180
	v_mov_b64_e32 v[2:3], v[18:19]
	v_mov_b64_e32 v[4:5], v[20:21]
	v_cndmask_b32_e32 v179, 0, v180, vcc
	v_cmp_gt_f32_e32 vcc, v180, v172
	v_mov_b64_e32 v[6:7], v[22:23]
	v_mov_b64_e32 v[8:9], v[24:25]
	v_mov_b64_e32 v[10:11], v[26:27]
	v_mov_b64_e32 v[12:13], v[28:29]
	v_mov_b64_e32 v[14:15], v[30:31]
	v_mov_b64_e32 v[16:17], v[32:33]
	v_mov_b64_e32 v[56:57], v[40:41]
	v_mov_b64_e32 v[54:55], v[38:39]
	v_mov_b64_e32 v[52:53], v[36:37]
	v_mov_b64_e32 v[50:51], v[34:35]
	s_cbranch_vccz .LBB0_307
	v_sub_f32_e32 v2, v172, v179
	v_exp_f32_e32 v2, v2
	v_mov_b32_e32 v173, v180
	v_mul_f32_e32 v176, v149, v2
	v_pk_mul_f32 v[64:65], v[48:49], v[2:3] op_sel_hi:[1,0]
	v_pk_mul_f32 v[62:63], v[46:47], v[2:3] op_sel_hi:[1,0]
	v_pk_mul_f32 v[60:61], v[44:45], v[2:3] op_sel_hi:[1,0]
	v_pk_mul_f32 v[58:59], v[42:43], v[2:3] op_sel_hi:[1,0]
	v_pk_mul_f32 v[56:57], v[40:41], v[2:3] op_sel_hi:[1,0]
	v_pk_mul_f32 v[54:55], v[38:39], v[2:3] op_sel_hi:[1,0]
	v_pk_mul_f32 v[52:53], v[36:37], v[2:3] op_sel_hi:[1,0]
	v_pk_mul_f32 v[50:51], v[34:35], v[2:3] op_sel_hi:[1,0]
	v_pk_mul_f32 v[16:17], v[32:33], v[2:3] op_sel_hi:[1,0]
	v_pk_mul_f32 v[14:15], v[30:31], v[2:3] op_sel_hi:[1,0]
	v_pk_mul_f32 v[12:13], v[28:29], v[2:3] op_sel_hi:[1,0]
	v_pk_mul_f32 v[10:11], v[26:27], v[2:3] op_sel_hi:[1,0]
	v_pk_mul_f32 v[8:9], v[24:25], v[2:3] op_sel_hi:[1,0]
	v_pk_mul_f32 v[6:7], v[22:23], v[2:3] op_sel_hi:[1,0]
	v_pk_mul_f32 v[4:5], v[20:21], v[2:3] op_sel_hi:[1,0]
	v_pk_mul_f32 v[2:3], v[18:19], v[2:3] op_sel_hi:[1,0]
.LBB0_307:
	v_sub_f32_e32 v174, v174, v179
	v_sub_f32_e32 v175, v175, v179
	v_exp_f32_e32 v174, v174
	v_exp_f32_e32 v175, v175
	v_sub_f32_e32 v178, v178, v179
	v_sub_f32_e32 v177, v177, v179
	v_cndmask_b32_e64 v180, 0, v174, s[42:43]
	v_cndmask_b32_e64 v181, 0, v174, s[40:41]
	v_cndmask_b32_e64 v182, 0, v174, s[38:39]
	v_cndmask_b32_e64 v183, 0, v174, s[44:45]
	v_cndmask_b32_e64 v184, 0, v175, s[42:43]
	v_cndmask_b32_e64 v185, 0, v175, s[40:41]
	v_cndmask_b32_e64 v186, 0, v175, s[38:39]
	v_cndmask_b32_e64 v187, 0, v175, s[44:45]
	v_exp_f32_e32 v189, v178
	v_cvt_pk_bf16_f32 v178, v180, v181
	v_cvt_pk_bf16_f32 v179, v182, v183
	v_cvt_pk_bf16_f32 v180, v184, v185
	v_cvt_pk_bf16_f32 v181, v186, v187
	v_exp_f32_e32 v177, v177
	v_cndmask_b32_e64 v193, 0, v189, s[42:43]
	v_mfma_f32_32x32x16_bf16 v[50:65], v[94:97], v[178:181], v[50:65]
	v_cndmask_b32_e64 v184, 0, v189, s[40:41]
	v_cndmask_b32_e64 v188, 0, v177, s[42:43]
	v_cndmask_b32_e64 v190, 0, v177, s[40:41]
	v_cndmask_b32_e64 v191, 0, v177, s[38:39]
	v_cndmask_b32_e64 v192, 0, v177, s[44:45]
	v_cndmask_b32_e64 v185, 0, v189, s[38:39]
	v_cndmask_b32_e64 v186, 0, v189, s[44:45]
	v_mfma_f32_32x32x16_bf16 v[2:17], v[86:89], v[178:181], v[2:17]
	v_cvt_pk_bf16_f32 v182, v188, v190
	v_cvt_pk_bf16_f32 v183, v191, v192
	v_cvt_pk_bf16_f32 v184, v193, v184
	v_cvt_pk_bf16_f32 v185, v185, v186
	v_add_f32_e32 v174, 0, v174
	v_add_f32_e32 v174, v175, v174
	v_add_f32_e32 v174, v177, v174
	v_mfma_f32_32x32x16_bf16 v[50:65], v[90:93], v[182:185], v[50:65]
	v_add_f32_e32 v174, v189, v174
	v_add_f32_e32 v174, v174, v176
	v_mfma_f32_32x32x16_bf16 v[2:17], v[82:85], v[182:185], v[2:17]
	s_setprio 0
	s_branch .LBB0_313
; #define LAS __attribute__((address_space(3)))
; #define MFMA32(a, b, c) __builtin_amdgcn_mfma_f32_32x32x16_bf16((a), (b), (c), 0, 0, 0)
; template <int MODE, bool UNI>
; DI void attn_compute(const bf16x8 (&qf)[4], const bf16x8 (&kf)[4], const bf16x8 (&vf)[2][2], int kt, int d00, const float* lut, float ubias, AttnSt& st,
;                      unsigned W, int win, int dmask, bool lane_sel) {
;     const int s0 = kt * 32;
;     const int d0 = d00 - s0;
;     const LAS float* lb = (const LAS float*)lut + ((MODE == 4) ? 16 * (d0 - 23) : (d0 - 23));
;     float bia[16];
;     if (!UNI) {
; #pragma unroll
;         for (int i = 0; i < 16; ++i) { const int ci = 16 * (i >> 3) + (i & 7); bia[i] = (MODE == 4) ? lb[16 * (23 - ci)] : lb[23 - ci]; }
;     }
;     f32x16 sx;
; #pragma unroll
;     for (int i = 0; i < 16; ++i) sx[i] = 0.f;
; #pragma unroll
;     for (int ks = 0; ks < 4; ++ks) sx = MFMA32(kf[ks], qf[ks], sx);
;     asm volatile("s_waitcnt lgkmcnt(0)" ::: "memory");
;     float sv[16]; float mx = NEGF;
; #pragma unroll
;     for (int i = 0; i < 16; ++i) {
;         const int ci = 16 * (i >> 3) + (i & 7);
;         const int dist = d0 - ci;
;         bool v;
;         if (MODE == 0) v = ((W >> ci) & 1u) != 0u;
;         else if (MODE == 1) v = ((unsigned)dist <= (unsigned)win) && ((dist & dmask) == 0);
;         else if (MODE == 2) v = lane_sel;
;         else v = dist >= 0;
;         const float bias = UNI ? ubias : bia[i];
;         float s = fmaf(sx[i], SC2, bias);
;         if (MODE == 0) { const unsigned t = (unsigned)__builtin_amdgcn_sbfe((int)W, ci, 1);
;             s = __uint_as_float((__float_as_uint(s) & t) | (__float_as_uint(NEGF) & ~t)); }
;         else s = v ? s : NEGF;
;         sv[i] = s; mx = fmaxf(mx, s);
;     }
;     mx = fmaxf(mx, __shfl_xor(mx, 32));
;     const float mnew = fmaxf(st.m, mx);
;     const float msafe = (mnew > -1e29f) ? mnew : 0.f;
;     if (__ballot(mnew > st.m) != 0ull) {
;         const float alpha = __builtin_amdgcn_exp2f(st.m - msafe);
;         st.l *= alpha; st.m = mnew;
; #pragma unroll
;         for (int i = 0; i < 16; ++i) { st.o0[i] *= alpha; st.o1[i] *= alpha; }
;     }
.LBB0_308:
	s_and_b64 vcc, exec, s[46:47]
	s_cbranch_vccz .LBB0_313
	s_waitcnt lgkmcnt(0)
	s_setprio 1
	v_mfma_f32_32x32x16_bf16 v[2:17], v[106:109], v[78:81], 0
	ds_read2_b32 v[50:51], v169 offset0:22 offset1:23
	ds_read2_b32 v[52:53], v169 offset0:20 offset1:21
	ds_read2_b32 v[54:55], v169 offset0:18 offset1:19
	ds_read2_b32 v[56:57], v169 offset0:16 offset1:17
	v_add_u32_e32 v106, 0x98, v170
	v_cmp_gt_u32_e32 vcc, s95, v106
	v_add_u32_e32 v107, 18, v170
	ds_read2_b32 v[58:59], v169 offset0:6 offset1:7
	ds_read2_b32 v[60:61], v169 offset0:4 offset1:5
	ds_read2_b32 v[62:63], v169 offset0:2 offset1:3
	ds_read2_b32 v[64:65], v169 offset1:1
	v_mfma_f32_32x32x16_bf16 v[2:17], v[110:113], v[74:77], v[2:17]
	v_mfma_f32_32x32x16_bf16 v[2:17], v[102:105], v[70:73], v[2:17]
	v_add_u32_e32 v102, 22, v170
	v_add_u32_e32 v103, 21, v170
	v_add_u32_e32 v104, 20, v170
	v_add_u32_e32 v105, 19, v170
	v_mfma_f32_32x32x16_bf16 v[2:17], v[98:101], v[66:69], v[2:17]
	s_waitcnt lgkmcnt(0)
	s_nop 10
	v_fmamk_f32 v2, v2, 0x3e38aa3b, v51
	v_fmac_f32_e32 v50, 0x3e38aa3b, v3
	v_cndmask_b32_e32 v3, v239, v2, vcc
	v_cmp_lt_u32_e32 vcc, s13, v102
	v_fmamk_f32 v51, v4, 0x3e38aa3b, v53
	v_fmac_f32_e32 v52, 0x3e38aa3b, v5
	v_cndmask_b32_e32 v4, v239, v50, vcc
	v_cmp_lt_u32_e32 vcc, s13, v103
	v_fmamk_f32 v6, v6, 0x3e38aa3b, v55
	v_fmac_f32_e32 v54, 0x3e38aa3b, v7
	v_cndmask_b32_e32 v5, v239, v51, vcc
	v_cmp_lt_u32_e32 vcc, s13, v104
	v_add_u32_e32 v51, 17, v170
	v_fmamk_f32 v8, v8, 0x3e38aa3b, v57
	v_cndmask_b32_e32 v2, v239, v52, vcc
	v_cmp_lt_u32_e32 vcc, s13, v105
	v_fmac_f32_e32 v56, 0x3e38aa3b, v9
	v_fmamk_f32 v10, v10, 0x3e38aa3b, v59
	v_cndmask_b32_e32 v7, v239, v6, vcc
	v_cmp_lt_u32_e32 vcc, s13, v107
	v_max3_f32 v6, v3, s30, v4
	v_fmac_f32_e32 v58, 0x3e38aa3b, v11
	v_cndmask_b32_e32 v50, v239, v54, vcc
	v_cmp_lt_u32_e32 vcc, s13, v51
	v_max3_f32 v6, v6, v5, v2
	v_fmamk_f32 v12, v12, 0x3e38aa3b, v61
	v_cndmask_b32_e32 v51, v239, v8, vcc
	v_add_u32_e32 v8, 16, v170
	v_cmp_lt_u32_e32 vcc, s13, v8
	v_add_u32_e32 v8, 7, v170
	v_max3_f32 v6, v6, v7, v50
	v_cndmask_b32_e32 v9, v239, v56, vcc
	v_cmp_lt_u32_e32 vcc, s13, v8
	v_add_u32_e32 v8, 6, v170
	v_fmac_f32_e32 v60, 0x3e38aa3b, v13
	v_cndmask_b32_e32 v10, v239, v10, vcc
	v_cmp_lt_u32_e32 vcc, s13, v8
	v_add_u32_e32 v8, 5, v170
	v_max3_f32 v6, v6, v51, v9
	v_cndmask_b32_e32 v11, v239, v58, vcc
	v_cmp_lt_u32_e32 vcc, s13, v8
	v_add_u32_e32 v8, 4, v170
	v_fmamk_f32 v14, v14, 0x3e38aa3b, v63
	v_cndmask_b32_e32 v12, v239, v12, vcc
	v_cmp_lt_u32_e32 vcc, s13, v8
	v_add_u32_e32 v8, 3, v170
	v_max3_f32 v6, v6, v10, v11
	v_cndmask_b32_e32 v13, v239, v60, vcc
	v_cmp_lt_u32_e32 vcc, s13, v8
	v_add_u32_e32 v8, 2, v170
	v_fmac_f32_e32 v62, 0x3e38aa3b, v15
	v_cndmask_b32_e32 v14, v239, v14, vcc
	v_cmp_lt_u32_e32 vcc, s13, v8
	v_max3_f32 v6, v6, v12, v13
	v_fmamk_f32 v16, v16, 0x3e38aa3b, v65
	v_cndmask_b32_e32 v15, v239, v62, vcc
	v_max3_f32 v8, v6, v14, v15
	v_add_u32_e32 v6, 1, v170
	v_cmp_lt_u32_e32 vcc, s13, v6
	v_fmac_f32_e32 v64, 0x3e38aa3b, v17
	s_nop 0
	v_cndmask_b32_e32 v16, v239, v16, vcc
	v_cmp_lt_u32_e32 vcc, s13, v170
	s_nop 1
	v_cndmask_b32_e32 v6, v239, v64, vcc
	v_max3_f32 v8, v8, v16, v6
	v_mov_b32_e32 v17, v8
	s_nop 1
	v_permlane32_swap_b32_e32 v17, v8
	s_waitcnt lgkmcnt(0)
	v_max3_f32 v173, v172, v8, v17
	v_cmp_lt_f32_e32 vcc, s12, v173
	s_nop 1
	v_cndmask_b32_e32 v8, 0, v173, vcc
	v_cmp_gt_f32_e32 vcc, v173, v172
	s_cbranch_vccz .LBB0_311
	v_sub_f32_e32 v17, v172, v8
	v_exp_f32_e32 v52, v17
	s_nop 0
	v_mul_f32_e32 v149, v149, v52
	v_pk_mul_f32 v[48:49], v[48:49], v[52:53] op_sel_hi:[1,0]
	v_pk_mul_f32 v[46:47], v[46:47], v[52:53] op_sel_hi:[1,0]
	v_pk_mul_f32 v[44:45], v[44:45], v[52:53] op_sel_hi:[1,0]
	v_pk_mul_f32 v[42:43], v[42:43], v[52:53] op_sel_hi:[1,0]
	v_pk_mul_f32 v[40:41], v[40:41], v[52:53] op_sel_hi:[1,0]
	v_pk_mul_f32 v[38:39], v[38:39], v[52:53] op_sel_hi:[1,0]
	v_pk_mul_f32 v[36:37], v[36:37], v[52:53] op_sel_hi:[1,0]
	v_pk_mul_f32 v[34:35], v[34:35], v[52:53] op_sel_hi:[1,0]
	v_pk_mul_f32 v[32:33], v[32:33], v[52:53] op_sel_hi:[1,0]
	v_pk_mul_f32 v[30:31], v[30:31], v[52:53] op_sel_hi:[1,0]
	v_pk_mul_f32 v[28:29], v[28:29], v[52:53] op_sel_hi:[1,0]
	v_pk_mul_f32 v[26:27], v[26:27], v[52:53] op_sel_hi:[1,0]
	v_pk_mul_f32 v[24:25], v[24:25], v[52:53] op_sel_hi:[1,0]
	v_pk_mul_f32 v[22:23], v[22:23], v[52:53] op_sel_hi:[1,0]
	v_pk_mul_f32 v[20:21], v[20:21], v[52:53] op_sel_hi:[1,0]
	v_pk_mul_f32 v[18:19], v[18:19], v[52:53] op_sel_hi:[1,0]
	s_branch .LBB0_312

; DI unsigned pk2(float lo, float hi) { f32x2 v = {lo, hi}; bf2_t b = __builtin_convertvector(v, bf2_t); return __builtin_bit_cast(unsigned, b); }
; #define MFMA32(a, b, c) __builtin_amdgcn_mfma_f32_32x32x16_bf16((a), (b), (c), 0, 0, 0)
; template <int MODE, bool UNI>
; DI void attn_compute(const bf16x8 (&qf)[4], const bf16x8 (&kf)[4], const bf16x8 (&vf)[2][2], int kt, int d00, const float* lut, float ubias, AttnSt& st,
;                      unsigned W, int win, int dmask, bool lane_sel) {
;     ...
;     float ps = 0.f; float p[16];
; #pragma unroll
;     for (int i = 0; i < 16; ++i) { const float e = __builtin_amdgcn_exp2f(sv[i] - msafe); p[i] = e; ps += e; }
;     st.l += ps;
;     u32x4 w0, w1;
;     w0.x = pk2(p[0], p[1]); w0.y = pk2(p[2], p[3]); w0.z = pk2(p[4], p[5]); w0.w = pk2(p[6], p[7]);
;     w1.x = pk2(p[8], p[9]); w1.y = pk2(p[10], p[11]); w1.z = pk2(p[12], p[13]); w1.w = pk2(p[14], p[15]);
;     const bf16x8 pf0 = __builtin_bit_cast(bf16x8, w0), pf1 = __builtin_bit_cast(bf16x8, w1);
;     st.o0 = MFMA32(vf[0][0], pf0, st.o0); st.o0 = MFMA32(vf[0][1], pf1, st.o0);
;     st.o1 = MFMA32(vf[1][0], pf0, st.o1); st.o1 = MFMA32(vf[1][1], pf1, st.o1);
.LBB0_312:
	v_sub_f32_e32 v2, v2, v8
	v_exp_f32_e32 v52, v2
	v_sub_f32_e32 v2, v7, v8
	v_exp_f32_e32 v53, v2
	v_sub_f32_e32 v2, v50, v8
	v_exp_f32_e32 v50, v2
	v_sub_f32_e32 v2, v51, v8
	v_sub_f32_e32 v3, v3, v8
	v_exp_f32_e32 v51, v2
	v_sub_f32_e32 v2, v9, v8
	v_exp_f32_e32 v3, v3
	v_sub_f32_e32 v4, v4, v8
	v_exp_f32_e32 v54, v2
	v_sub_f32_e32 v2, v10, v8
	v_exp_f32_e32 v4, v4
	v_sub_f32_e32 v5, v5, v8
	v_exp_f32_e32 v10, v2
	v_sub_f32_e32 v2, v11, v8
	v_exp_f32_e32 v5, v5
	v_exp_f32_e32 v11, v2
	v_sub_f32_e32 v2, v12, v8
	v_exp_f32_e32 v12, v2
	v_sub_f32_e32 v2, v13, v8
	v_add_f32_e32 v17, 0, v3
	v_exp_f32_e32 v13, v2
	v_sub_f32_e32 v2, v14, v8
	v_add_f32_e32 v17, v4, v17
	v_exp_f32_e32 v14, v2
	v_sub_f32_e32 v2, v15, v8
	v_add_f32_e32 v17, v5, v17
	v_exp_f32_e32 v15, v2
	v_cvt_pk_bf16_f32 v2, v3, v4
	v_cvt_pk_bf16_f32 v3, v5, v52
	v_cvt_pk_bf16_f32 v4, v53, v50
	v_cvt_pk_bf16_f32 v5, v51, v54
	v_sub_f32_e32 v7, v16, v8
	v_sub_f32_e32 v6, v6, v8
	v_mfma_f32_32x32x16_bf16 v[34:49], v[94:97], v[2:5], v[34:49]
	v_exp_f32_e32 v16, v7
	v_exp_f32_e32 v55, v6
	v_add_f32_e32 v17, v52, v17
	v_add_f32_e32 v17, v53, v17
	v_add_f32_e32 v17, v50, v17
	v_add_f32_e32 v17, v51, v17
	v_cvt_pk_bf16_f32 v6, v10, v11
	v_mfma_f32_32x32x16_bf16 v[18:33], v[86:89], v[2:5], v[18:33]
	v_cvt_pk_bf16_f32 v7, v12, v13
	v_cvt_pk_bf16_f32 v8, v14, v15
	v_cvt_pk_bf16_f32 v9, v16, v55
	v_add_f32_e32 v17, v54, v17
	v_add_f32_e32 v10, v10, v17
	v_add_f32_e32 v10, v11, v10
	v_add_f32_e32 v2, v12, v10
	v_mfma_f32_32x32x16_bf16 v[34:49], v[90:93], v[6:9], v[34:49]
	v_add_f32_e32 v2, v13, v2
	v_add_f32_e32 v2, v14, v2
	v_add_f32_e32 v2, v15, v2
	v_add_f32_e32 v2, v16, v2
	v_add_f32_e32 v2, v55, v2
	v_add_f32_e32 v174, v2, v149
	s_nop 5
	v_mov_b64_e32 v[64:65], v[48:49]
	v_mfma_f32_32x32x16_bf16 v[18:33], v[82:85], v[6:9], v[18:33]
	s_setprio 0
	v_mov_b64_e32 v[62:63], v[46:47]
	v_mov_b64_e32 v[60:61], v[44:45]
	v_mov_b64_e32 v[58:59], v[42:43]
	v_mov_b64_e32 v[56:57], v[40:41]
	v_mov_b64_e32 v[54:55], v[38:39]
	v_mov_b64_e32 v[52:53], v[36:37]
	v_mov_b64_e32 v[50:51], v[34:35]
	s_nop 4
	v_mov_b64_e32 v[2:3], v[18:19]
	v_mov_b64_e32 v[4:5], v[20:21]
	v_mov_b64_e32 v[6:7], v[22:23]
	v_mov_b64_e32 v[8:9], v[24:25]
	v_mov_b64_e32 v[10:11], v[26:27]
	v_mov_b64_e32 v[12:13], v[28:29]
	v_mov_b64_e32 v[14:15], v[30:31]
	v_mov_b64_e32 v[16:17], v[32:33]

; #define LAS __attribute__((address_space(3)))
; #define MFMA32(a, b, c) __builtin_amdgcn_mfma_f32_32x32x16_bf16((a), (b), (c), 0, 0, 0)
; template <int MODE, bool UNI>
; DI void attn_compute(const bf16x8 (&qf)[4], const bf16x8 (&kf)[4], const bf16x8 (&vf)[2][2], int kt, int d00, const float* lut, float ubias, AttnSt& st,
;                      unsigned W, int win, int dmask, bool lane_sel) {
;     const int s0 = kt * 32;
;     const int d0 = d00 - s0;
;     const LAS float* lb = (const LAS float*)lut + ((MODE == 4) ? 16 * (d0 - 23) : (d0 - 23));
;     float bia[16];
;     if (!UNI) {
; #pragma unroll
;         for (int i = 0; i < 16; ++i) { const int ci = 16 * (i >> 3) + (i & 7); bia[i] = (MODE == 4) ? lb[16 * (23 - ci)] : lb[23 - ci]; }
;     }
;     f32x16 sx;
; #pragma unroll
;     for (int i = 0; i < 16; ++i) sx[i] = 0.f;
; #pragma unroll
;     for (int ks = 0; ks < 4; ++ks) sx = MFMA32(kf[ks], qf[ks], sx);
;     asm volatile("s_waitcnt lgkmcnt(0)" ::: "memory");
;     float sv[16]; float mx = NEGF;
; #pragma unroll
;     for (int i = 0; i < 16; ++i) {
;         const int ci = 16 * (i >> 3) + (i & 7);
;         const int dist = d0 - ci;
;         bool v;
;         if (MODE == 0) v = ((W >> ci) & 1u) != 0u;
;         else if (MODE == 1) v = ((unsigned)dist <= (unsigned)win) && ((dist & dmask) == 0);
;         else if (MODE == 2) v = lane_sel;
;         else v = dist >= 0;
;         const float bias = UNI ? ubias : bia[i];
;         float s = fmaf(sx[i], SC2, bias);
;         if (MODE == 0) { const unsigned t = (unsigned)__builtin_amdgcn_sbfe((int)W, ci, 1);
;             s = __uint_as_float((__float_as_uint(s) & t) | (__float_as_uint(NEGF) & ~t)); }
;         else s = v ? s : NEGF;
;         sv[i] = s; mx = fmaxf(mx, s);
;     }
;     mx = fmaxf(mx, __shfl_xor(mx, 32));
;     const float mnew = fmaxf(st.m, mx);
;     const float msafe = (mnew > -1e29f) ? mnew : 0.f;
;     if (__ballot(mnew > st.m) != 0ull) {
;         const float alpha = __builtin_amdgcn_exp2f(st.m - msafe);
;         st.l *= alpha; st.m = mnew;
; #pragma unroll
;         for (int i = 0; i < 16; ++i) { st.o0[i] *= alpha; st.o1[i] *= alpha; }
;     }
.LBB0_324:
	s_waitcnt lgkmcnt(0)
	s_setprio 1
	v_mfma_f32_32x32x16_bf16 v[34:49], v[34:37], v[62:65], 0
	v_lshrrev_b32_e32 v150, v137, v106
	v_bfe_i32 v151, v150, 4, 1
	v_bfe_i32 v152, v150, 5, 1
	v_bfe_i32 v153, v150, 6, 1
	v_mfma_f32_32x32x16_bf16 v[34:49], v[90:93], v[58:61], v[34:49]
	ds_read2_b32 v[90:91], v103 offset0:22 offset1:23
	ds_read2_b32 v[92:93], v103 offset0:20 offset1:21
	ds_read2_b32 v[106:107], v103 offset0:18 offset1:19
	ds_read2_b32 v[108:109], v103 offset0:16 offset1:17
	ds_read2_b32 v[110:111], v103 offset0:6 offset1:7
	ds_read2_b32 v[112:113], v103 offset0:4 offset1:5
	ds_read2_b32 v[146:147], v103 offset0:2 offset1:3
	ds_read2_b32 v[148:149], v103 offset1:1
	v_mfma_f32_32x32x16_bf16 v[34:49], v[86:89], v[54:57], v[34:49]
	v_bfe_i32 v88, v150, 2, 1
	v_bfe_i32 v86, v150, 0, 1
	v_bfe_i32 v87, v150, 1, 1
	v_bfe_i32 v89, v150, 3, 1
	v_mfma_f32_32x32x16_bf16 v[34:49], v[82:85], v[50:53], v[34:49]
	s_waitcnt lgkmcnt(0)
	s_nop 10
	v_fmac_f32_e32 v90, 0x3e38aa3b, v35
	v_fmamk_f32 v35, v36, 0x3e38aa3b, v93
	v_fmamk_f32 v36, v38, 0x3e38aa3b, v107
	v_bitop3_b32 v83, v35, s30, v88 bitop3:0xe4
	v_fmac_f32_e32 v108, 0x3e38aa3b, v41
	v_bfe_i32 v35, v150, 7, 1
	v_fmamk_f32 v34, v34, 0x3e38aa3b, v91
	v_fmac_f32_e32 v92, 0x3e38aa3b, v37
	v_fmac_f32_e32 v106, 0x3e38aa3b, v39
	v_fmamk_f32 v37, v40, 0x3e38aa3b, v109
	v_bitop3_b32 v39, v36, s30, v151 bitop3:0xe4
	v_bitop3_b32 v40, v108, s30, v35 bitop3:0xe4
	v_fmamk_f32 v35, v42, 0x3e38aa3b, v111
	v_bfe_i32 v36, v150, 16, 1
	v_bitop3_b32 v85, v34, s30, v86 bitop3:0xe4
	v_bitop3_b32 v84, v90, s30, v87 bitop3:0xe4
	v_bitop3_b32 v41, v35, s30, v36 bitop3:0xe4
	v_fmac_f32_e32 v110, 0x3e38aa3b, v43
	v_bfe_i32 v35, v150, 17, 1
	v_bitop3_b32 v82, v92, s30, v89 bitop3:0xe4
	v_max3_f32 v34, v85, s30, v84
	v_bitop3_b32 v42, v110, s30, v35 bitop3:0xe4
	v_fmamk_f32 v35, v44, 0x3e38aa3b, v113
	v_bfe_i32 v36, v150, 18, 1
	v_bitop3_b32 v38, v106, s30, v152 bitop3:0xe4
	v_max3_f32 v34, v34, v83, v82
	v_bitop3_b32 v43, v35, s30, v36 bitop3:0xe4
	v_fmac_f32_e32 v112, 0x3e38aa3b, v45
	v_bfe_i32 v35, v150, 19, 1
	v_bitop3_b32 v37, v37, s30, v153 bitop3:0xe4
	v_max3_f32 v34, v34, v39, v38
	v_bitop3_b32 v44, v112, s30, v35 bitop3:0xe4
	v_fmamk_f32 v35, v46, 0x3e38aa3b, v147
	v_bfe_i32 v36, v150, 20, 1
	v_max3_f32 v34, v34, v37, v40
	v_bitop3_b32 v45, v35, s30, v36 bitop3:0xe4
	v_fmac_f32_e32 v146, 0x3e38aa3b, v47
	v_bfe_i32 v35, v150, 21, 1
	v_max3_f32 v34, v34, v41, v42
	v_bitop3_b32 v46, v146, s30, v35 bitop3:0xe4
	v_fmamk_f32 v35, v48, 0x3e38aa3b, v149
	v_bfe_i32 v36, v150, 22, 1
	v_max3_f32 v34, v34, v43, v44
	v_bitop3_b32 v47, v35, s30, v36 bitop3:0xe4
	v_fmac_f32_e32 v148, 0x3e38aa3b, v49
	v_bfe_i32 v35, v150, 23, 1
	v_max3_f32 v34, v34, v45, v46
	v_bitop3_b32 v35, v148, s30, v35 bitop3:0xe4
	v_max3_f32 v34, v34, v47, v35
	v_mov_b32_e32 v36, v34
	s_nop 1
	v_permlane32_swap_b32_e32 v36, v34
	s_waitcnt lgkmcnt(0)
	v_max3_f32 v34, v105, v34, v36
	v_cmp_lt_f32_e32 vcc, s12, v34
	s_nop 1
	v_cndmask_b32_e32 v36, 0, v34, vcc
	v_cmp_gt_f32_e32 vcc, v34, v105
	s_cbranch_vccz .LBB0_326
	v_sub_f32_e32 v48, v105, v36
	v_exp_f32_e32 v48, v48
	s_nop 0
	v_mul_f32_e32 v102, v102, v48
	v_pk_mul_f32 v[32:33], v[32:33], v[48:49] op_sel_hi:[1,0]
	v_pk_mul_f32 v[30:31], v[30:31], v[48:49] op_sel_hi:[1,0]
	v_pk_mul_f32 v[28:29], v[28:29], v[48:49] op_sel_hi:[1,0]
	v_pk_mul_f32 v[26:27], v[26:27], v[48:49] op_sel_hi:[1,0]
	v_pk_mul_f32 v[24:25], v[24:25], v[48:49] op_sel_hi:[1,0]
	v_pk_mul_f32 v[22:23], v[22:23], v[48:49] op_sel_hi:[1,0]
	v_pk_mul_f32 v[20:21], v[20:21], v[48:49] op_sel_hi:[1,0]
	v_pk_mul_f32 v[18:19], v[18:19], v[48:49] op_sel_hi:[1,0]
	v_pk_mul_f32 v[16:17], v[16:17], v[48:49] op_sel_hi:[1,0]
	v_pk_mul_f32 v[14:15], v[14:15], v[48:49] op_sel_hi:[1,0]
	v_pk_mul_f32 v[12:13], v[12:13], v[48:49] op_sel_hi:[1,0]
	v_pk_mul_f32 v[10:11], v[10:11], v[48:49] op_sel_hi:[1,0]
	v_pk_mul_f32 v[8:9], v[8:9], v[48:49] op_sel_hi:[1,0]
	v_pk_mul_f32 v[6:7], v[6:7], v[48:49] op_sel_hi:[1,0]
	v_pk_mul_f32 v[4:5], v[4:5], v[48:49] op_sel_hi:[1,0]
	v_pk_mul_f32 v[2:3], v[2:3], v[48:49] op_sel_hi:[1,0]
	s_branch .LBB0_327

; #define LAS __attribute__((address_space(3)))
; template <int MODE, bool UNI>
; DI void attn_compute(const bf16x8 (&qf)[4], const bf16x8 (&kf)[4], const bf16x8 (&vf)[2][2], int kt, int d00, const float* lut, float ubias, AttnSt& st,
;                      unsigned W, int win, int dmask, bool lane_sel) {
;     ...
;     float ps = 0.f; float p[16];
; #pragma unroll
;     for (int i = 0; i < 16; ++i) { const float e = __builtin_amdgcn_exp2f(sv[i] - msafe); p[i] = e; ps += e; }
;     st.l += ps;
;     u32x4 w0, w1;
;     w0.x = pk2(p[0], p[1]); w0.y = pk2(p[2], p[3]); w0.z = pk2(p[4], p[5]); w0.w = pk2(p[6], p[7]);
;     w1.x = pk2(p[8], p[9]); w1.y = pk2(p[10], p[11]); w1.z = pk2(p[12], p[13]); w1.w = pk2(p[14], p[15]);
;     const bf16x8 pf0 = __builtin_bit_cast(bf16x8, w0), pf1 = __builtin_bit_cast(bf16x8, w1);
;     st.o0 = MFMA32(vf[0][0], pf0, st.o0); st.o0 = MFMA32(vf[0][1], pf1, st.o0);
;     st.o1 = MFMA32(vf[1][0], pf0, st.o1); st.o1 = MFMA32(vf[1][1], pf1, st.o1);
; template <int MODE>
; DI void attn_range(const AttnCtx& c, const bf16x8 (&qf)[4], int lo, int hi, int t0, int d00, AttnSt& st, const unsigned* maskrow, int h8, int win, int dmask, bool lane_sel) {
;     ...
;     for (int kt = lo; kt <= hi; ++kt) {
;         asm volatile("s_waitcnt vmcnt(0)" ::: "memory");
;         bf16x8 kf[4], vf[2][2];
; #pragma unroll
;         for (int ks = 0; ks < 4; ++ks) kf[ks] = *(const LAS bf16x8*)(c.wl + c.kfo[ks]);
; #pragma unroll
;         for (int mt = 0; mt < 2; ++mt)
; #pragma unroll
;             for (int s = 0; s < 2; ++s) vf[mt][s] = *(const LAS bf16x8*)(c.wl + 4096 + c.vfo[mt][s]);
;         const unsigned W = Wn >> h8;
;         const int dlo = t0 - kt * 32 - 31;
;         float ub = 0.f; bool uni = false;
;         if (dlo >= 182) { const unsigned ua = __builtin_amdgcn_readfirstlane(__float_as_uint(c.lut[dlo])), ue = __builtin_amdgcn_readfirstlane(__float_as_uint(c.lut[dlo + 62])); uni = (ua == ue); ub = __uint_as_float(ua); }
;         asm volatile("s_waitcnt lgkmcnt(0)" ::: "memory");
;         if (kt < hi) { attn_dma(c, kt + 1); if (MODE == 0) Wn = maskrow[kt + 1]; }
;         if (MODE == 1 && dmask != 0) attn_compute_sp4(qf, kf, vf, kt, d00, c.lut, st, win, dmask);
;         else attn_compute<MODE, false>(qf, kf, vf, kt, d00, c.lut, 0.f, st, W, win, dmask, lane_sel);
;     }
.LBB0_327:
	v_sub_f32_e32 v38, v38, v36
	v_exp_f32_e32 v86, v38
	v_sub_f32_e32 v38, v40, v36
	v_exp_f32_e32 v87, v38
	v_sub_f32_e32 v38, v41, v36
	v_sub_f32_e32 v48, v85, v36
	v_sub_f32_e32 v49, v84, v36
	v_sub_f32_e32 v83, v83, v36
	v_sub_f32_e32 v82, v82, v36
	v_sub_f32_e32 v39, v39, v36
	v_sub_f32_e32 v37, v37, v36
	v_exp_f32_e32 v88, v38
	v_sub_f32_e32 v38, v42, v36
	v_exp_f32_e32 v48, v48
	v_exp_f32_e32 v49, v49
	v_exp_f32_e32 v83, v83
	v_exp_f32_e32 v82, v82
	v_exp_f32_e32 v85, v39
	v_exp_f32_e32 v37, v37
	v_exp_f32_e32 v89, v38
	v_sub_f32_e32 v38, v43, v36
	v_exp_f32_e32 v90, v38
	v_sub_f32_e32 v38, v44, v36
	v_exp_f32_e32 v91, v38
	v_sub_f32_e32 v38, v45, v36
	v_exp_f32_e32 v92, v38
	v_sub_f32_e32 v38, v46, v36
	v_add_f32_e32 v84, 0, v48
	v_exp_f32_e32 v46, v38
	v_cvt_pk_bf16_f32 v38, v48, v49
	v_cvt_pk_bf16_f32 v39, v83, v82
	v_cvt_pk_bf16_f32 v40, v85, v86
	v_cvt_pk_bf16_f32 v41, v37, v87
	v_add_f32_e32 v84, v49, v84
	v_add_f32_e32 v84, v83, v84
	v_mfma_f32_32x32x16_bf16 v[18:33], v[78:81], v[38:41], v[18:33]
	v_sub_f32_e32 v42, v47, v36
	v_sub_f32_e32 v35, v35, v36
	v_add_f32_e32 v36, v82, v84
	v_exp_f32_e32 v47, v42
	v_exp_f32_e32 v35, v35
	v_add_f32_e32 v36, v85, v36
	v_add_f32_e32 v36, v86, v36
	v_mfma_f32_32x32x16_bf16 v[2:17], v[70:73], v[38:41], v[2:17]
	v_add_f32_e32 v36, v37, v36
	v_add_f32_e32 v36, v87, v36
	v_cvt_pk_bf16_f32 v42, v88, v89
	v_cvt_pk_bf16_f32 v43, v90, v91
	v_cvt_pk_bf16_f32 v44, v92, v46
	v_cvt_pk_bf16_f32 v45, v47, v35
	v_add_f32_e32 v36, v88, v36
	v_add_f32_e32 v36, v89, v36
	v_mfma_f32_32x32x16_bf16 v[18:33], v[74:77], v[42:45], v[18:33]
	v_add_f32_e32 v36, v90, v36
	v_add_f32_e32 v36, v91, v36
	v_add_f32_e32 v36, v92, v36
	v_add_f32_e32 v36, v46, v36
	v_add_f32_e32 v36, v47, v36
	v_add_f32_e32 v35, v35, v36
	s_add_i32 s60, s60, 1
	v_mfma_f32_32x32x16_bf16 v[2:17], v[66:69], v[42:45], v[2:17]
	s_setprio 0
	s_add_i32 s2, s2, 32
	v_add_f32_e32 v102, v35, v102
	v_lshl_add_u64 v[100:101], v[100:101], 0, 4
	s_cmp_lg_u32 s59, s60
	v_add_u32_e32 v103, 0xffffff80, v103
	s_cbranch_scc0 .LBB0_329
	v_mov_b32_e32 v105, v34
	s_and_b32 s61, s60, 3
	s_cbranch_scc1 .Lmk_rot
	s_waitcnt vmcnt(0)
	v_mov_b32_e32 v198, v224
	v_mov_b32_e32 v199, v225
	v_mov_b32_e32 v200, v226
	v_mov_b32_e32 v201, v227
	s_branch .Lmk_done

; #define LAS __attribute__((address_space(3)))
; #define MFMA32(a, b, c) __builtin_amdgcn_mfma_f32_32x32x16_bf16((a), (b), (c), 0, 0, 0)
; template <int MODE, bool UNI>
; DI void attn_compute(const bf16x8 (&qf)[4], const bf16x8 (&kf)[4], const bf16x8 (&vf)[2][2], int kt, int d00, const float* lut, float ubias, AttnSt& st,
;                      unsigned W, int win, int dmask, bool lane_sel) {
;     const int s0 = kt * 32;
;     const int d0 = d00 - s0;
;     const LAS float* lb = (const LAS float*)lut + ((MODE == 4) ? 16 * (d0 - 23) : (d0 - 23));
;     float bia[16];
;     if (!UNI) {
; #pragma unroll
;         for (int i = 0; i < 16; ++i) { const int ci = 16 * (i >> 3) + (i & 7); bia[i] = (MODE == 4) ? lb[16 * (23 - ci)] : lb[23 - ci]; }
;     }
;     f32x16 sx;
; #pragma unroll
;     for (int i = 0; i < 16; ++i) sx[i] = 0.f;
; #pragma unroll
;     for (int ks = 0; ks < 4; ++ks) sx = MFMA32(kf[ks], qf[ks], sx);
;     asm volatile("s_waitcnt lgkmcnt(0)" ::: "memory");
;     float sv[16]; float mx = NEGF;
; #pragma unroll
;     for (int i = 0; i < 16; ++i) {
;         const int ci = 16 * (i >> 3) + (i & 7);
;         const int dist = d0 - ci;
;         bool v;
;         if (MODE == 0) v = ((W >> ci) & 1u) != 0u;
;         else if (MODE == 1) v = ((unsigned)dist <= (unsigned)win) && ((dist & dmask) == 0);
;         else if (MODE == 2) v = lane_sel;
;         else v = dist >= 0;
;         const float bias = UNI ? ubias : bia[i];
;         float s = fmaf(sx[i], SC2, bias);
;         if (MODE == 0) { const unsigned t = (unsigned)__builtin_amdgcn_sbfe((int)W, ci, 1);
;             s = __uint_as_float((__float_as_uint(s) & t) | (__float_as_uint(NEGF) & ~t)); }
;         else s = v ? s : NEGF;
;         sv[i] = s; mx = fmaxf(mx, s);
;     }
;     mx = fmaxf(mx, __shfl_xor(mx, 32));
;     const float mnew = fmaxf(st.m, mx);
;     const float msafe = (mnew > -1e29f) ? mnew : 0.f;
;     if (__ballot(mnew > st.m) != 0ull) {
;         const float alpha = __builtin_amdgcn_exp2f(st.m - msafe);
;         st.l *= alpha; st.m = mnew;
; #pragma unroll
;         for (int i = 0; i < 16; ++i) { st.o0[i] *= alpha; st.o1[i] *= alpha; }
;     }
.LBB0_349:
	s_waitcnt lgkmcnt(0)
	s_setprio 1
	v_mfma_f32_32x32x16_bf16 v[50:65], v[50:53], v[70:73], 0
	v_add_u32_e32 v0, s65, v105
	v_mfma_f32_32x32x16_bf16 v[50:65], v[90:93], v[66:69], v[50:65]
	v_mfma_f32_32x32x16_bf16 v[50:65], v[94:97], v[78:81], v[50:65]
	ds_read2_b32 v[14:15], v0 offset0:22 offset1:23
	ds_read2_b32 v[90:91], v0 offset0:20 offset1:21
	ds_read2_b32 v[92:93], v0 offset0:18 offset1:19
	ds_read2_b32 v[94:95], v0 offset0:16 offset1:17
	ds_read2_b32 v[96:97], v0 offset0:6 offset1:7
	ds_read2_b32 v[108:109], v0 offset0:4 offset1:5
	ds_read2_b32 v[110:111], v0 offset0:2 offset1:3
	ds_read2_b32 v[112:113], v0 offset1:1
	v_mfma_f32_32x32x16_bf16 v[50:65], v[86:89], v[74:77], v[50:65]
	s_waitcnt lgkmcnt(0)
	s_nop 10
	v_fmamk_f32 v0, v50, 0x3e38aa3b, v15
	v_fmac_f32_e32 v14, 0x3e38aa3b, v51
	v_fmamk_f32 v15, v52, 0x3e38aa3b, v91
	v_fmac_f32_e32 v90, 0x3e38aa3b, v53
	v_cndmask_b32_e64 v89, v239, v0, s[0:1]
	v_cndmask_b32_e64 v88, v239, v14, s[0:1]
	v_fmamk_f32 v50, v54, 0x3e38aa3b, v93
	v_fmac_f32_e32 v92, 0x3e38aa3b, v55
	v_cndmask_b32_e64 v87, v239, v15, s[0:1]
	v_cndmask_b32_e64 v86, v239, v90, s[0:1]
	v_max3_f32 v0, v89, s30, v88
	v_fmamk_f32 v51, v56, 0x3e38aa3b, v95
	v_fmac_f32_e32 v94, 0x3e38aa3b, v57
	v_fmac_f32_e32 v96, 0x3e38aa3b, v59
	v_fmamk_f32 v53, v60, 0x3e38aa3b, v109
	v_cndmask_b32_e64 v60, v239, v50, s[0:1]
	v_cndmask_b32_e64 v59, v239, v92, s[0:1]
	v_max3_f32 v0, v0, v87, v86
	v_fmamk_f32 v52, v58, 0x3e38aa3b, v97
	v_cndmask_b32_e64 v58, v239, v51, s[0:1]
	v_cndmask_b32_e64 v57, v239, v94, s[0:1]
	v_max3_f32 v0, v0, v60, v59
	v_cndmask_b32_e64 v51, v239, v52, s[0:1]
	v_cndmask_b32_e64 v50, v239, v96, s[0:1]
	v_max3_f32 v0, v0, v58, v57
	v_fmac_f32_e32 v108, 0x3e38aa3b, v61
	v_max3_f32 v0, v0, v51, v50
	v_cndmask_b32_e64 v52, v239, v53, s[0:1]
	v_cndmask_b32_e64 v53, v239, v108, s[0:1]
	v_fmamk_f32 v14, v62, 0x3e38aa3b, v111
	v_fmac_f32_e32 v110, 0x3e38aa3b, v63
	v_max3_f32 v0, v0, v52, v53
	v_cndmask_b32_e64 v54, v239, v14, s[0:1]
	v_cndmask_b32_e64 v55, v239, v110, s[0:1]
	v_fmamk_f32 v14, v64, 0x3e38aa3b, v113
	v_fmac_f32_e32 v112, 0x3e38aa3b, v65
	v_max3_f32 v0, v0, v54, v55
	v_cndmask_b32_e64 v56, v239, v14, s[0:1]
	v_cndmask_b32_e64 v14, v239, v112, s[0:1]
	v_max3_f32 v0, v0, v56, v14
	v_mov_b32_e32 v15, v0
	s_nop 1
	v_permlane32_swap_b32_e32 v15, v0
	s_waitcnt lgkmcnt(0)
	v_max3_f32 v0, v106, v0, v15
	v_cmp_lt_f32_e32 vcc, s12, v0
	s_nop 1
	v_cndmask_b32_e32 v15, 0, v0, vcc
	v_cmp_gt_f32_e32 vcc, v0, v106
	s_cbranch_vccz .LBB0_351
	v_sub_f32_e32 v61, v106, v15
	v_exp_f32_e32 v62, v61
	s_nop 0
	v_mul_f32_e32 v48, v48, v62
	v_pk_mul_f32 v[46:47], v[46:47], v[62:63] op_sel_hi:[1,0]
	v_pk_mul_f32 v[44:45], v[44:45], v[62:63] op_sel_hi:[1,0]
	v_pk_mul_f32 v[42:43], v[42:43], v[62:63] op_sel_hi:[1,0]
	v_pk_mul_f32 v[40:41], v[40:41], v[62:63] op_sel_hi:[1,0]
	v_pk_mul_f32 v[38:39], v[38:39], v[62:63] op_sel_hi:[1,0]
	v_pk_mul_f32 v[36:37], v[36:37], v[62:63] op_sel_hi:[1,0]
	v_pk_mul_f32 v[34:35], v[34:35], v[62:63] op_sel_hi:[1,0]
	v_pk_mul_f32 v[32:33], v[32:33], v[62:63] op_sel_hi:[1,0]
	v_pk_mul_f32 v[30:31], v[30:31], v[62:63] op_sel_hi:[1,0]
	v_pk_mul_f32 v[28:29], v[28:29], v[62:63] op_sel_hi:[1,0]
	v_pk_mul_f32 v[26:27], v[26:27], v[62:63] op_sel_hi:[1,0]
	v_pk_mul_f32 v[24:25], v[24:25], v[62:63] op_sel_hi:[1,0]
	v_pk_mul_f32 v[22:23], v[22:23], v[62:63] op_sel_hi:[1,0]
	v_pk_mul_f32 v[20:21], v[20:21], v[62:63] op_sel_hi:[1,0]
	v_pk_mul_f32 v[18:19], v[18:19], v[62:63] op_sel_hi:[1,0]
	v_pk_mul_f32 v[16:17], v[16:17], v[62:63] op_sel_hi:[1,0]
	s_branch .LBB0_352

; #define LAS __attribute__((address_space(3)))
; template <int MODE, bool UNI>
; DI void attn_compute(const bf16x8 (&qf)[4], const bf16x8 (&kf)[4], const bf16x8 (&vf)[2][2], int kt, int d00, const float* lut, float ubias, AttnSt& st,
;                      unsigned W, int win, int dmask, bool lane_sel) {
;     ...
;     float ps = 0.f; float p[16];
; #pragma unroll
;     for (int i = 0; i < 16; ++i) { const float e = __builtin_amdgcn_exp2f(sv[i] - msafe); p[i] = e; ps += e; }
;     st.l += ps;
;     u32x4 w0, w1;
;     w0.x = pk2(p[0], p[1]); w0.y = pk2(p[2], p[3]); w0.z = pk2(p[4], p[5]); w0.w = pk2(p[6], p[7]);
;     w1.x = pk2(p[8], p[9]); w1.y = pk2(p[10], p[11]); w1.z = pk2(p[12], p[13]); w1.w = pk2(p[14], p[15]);
;     const bf16x8 pf0 = __builtin_bit_cast(bf16x8, w0), pf1 = __builtin_bit_cast(bf16x8, w1);
;     st.o0 = MFMA32(vf[0][0], pf0, st.o0); st.o0 = MFMA32(vf[0][1], pf1, st.o0);
;     st.o1 = MFMA32(vf[1][0], pf0, st.o1); st.o1 = MFMA32(vf[1][1], pf1, st.o1);
; template <int MODE>
; DI void attn_range(const AttnCtx& c, const bf16x8 (&qf)[4], int lo, int hi, int t0, int d00, AttnSt& st, const unsigned* maskrow, int h8, int win, int dmask, bool lane_sel) {
;     ...
;     for (int kt = lo; kt <= hi; ++kt) {
;         asm volatile("s_waitcnt vmcnt(0)" ::: "memory");
;         bf16x8 kf[4], vf[2][2];
; #pragma unroll
;         for (int ks = 0; ks < 4; ++ks) kf[ks] = *(const LAS bf16x8*)(c.wl + c.kfo[ks]);
; #pragma unroll
;         for (int mt = 0; mt < 2; ++mt)
; #pragma unroll
;             for (int s = 0; s < 2; ++s) vf[mt][s] = *(const LAS bf16x8*)(c.wl + 4096 + c.vfo[mt][s]);
;         const unsigned W = Wn >> h8;
;         const int dlo = t0 - kt * 32 - 31;
;         float ub = 0.f; bool uni = false;
;         if (dlo >= 182) { const unsigned ua = __builtin_amdgcn_readfirstlane(__float_as_uint(c.lut[dlo])), ue = __builtin_amdgcn_readfirstlane(__float_as_uint(c.lut[dlo + 62])); uni = (ua == ue); ub = __uint_as_float(ua); }
;         asm volatile("s_waitcnt lgkmcnt(0)" ::: "memory");
;         if (kt < hi) { attn_dma(c, kt + 1); if (MODE == 0) Wn = maskrow[kt + 1]; }
;         if (MODE == 1 && dmask != 0) attn_compute_sp4(qf, kf, vf, kt, d00, c.lut, st, win, dmask);
;         else attn_compute<MODE, false>(qf, kf, vf, kt, d00, c.lut, 0.f, st, W, win, dmask, lane_sel);
;     }
.LBB0_352:
	v_sub_f32_e32 v61, v89, v15
	v_exp_f32_e32 v61, v61
	v_sub_f32_e32 v62, v88, v15
	v_exp_f32_e32 v62, v62
	v_sub_f32_e32 v63, v87, v15
	v_sub_f32_e32 v65, v86, v15
	v_sub_f32_e32 v60, v60, v15
	v_sub_f32_e32 v59, v59, v15
	v_sub_f32_e32 v58, v58, v15
	v_sub_f32_e32 v57, v57, v15
	v_sub_f32_e32 v50, v50, v15
	v_exp_f32_e32 v63, v63
	v_exp_f32_e32 v65, v65
	v_exp_f32_e32 v60, v60
	v_exp_f32_e32 v59, v59
	v_exp_f32_e32 v58, v58
	v_exp_f32_e32 v86, v57
	v_exp_f32_e32 v88, v50
	v_sub_f32_e32 v50, v52, v15
	v_exp_f32_e32 v89, v50
	v_sub_f32_e32 v50, v53, v15
	v_add_f32_e32 v64, 0, v61
	v_exp_f32_e32 v90, v50
	v_sub_f32_e32 v50, v54, v15
	v_add_f32_e32 v64, v62, v64
	v_sub_f32_e32 v51, v51, v15
	v_exp_f32_e32 v91, v50
	v_sub_f32_e32 v50, v55, v15
	v_add_f32_e32 v64, v63, v64
	v_exp_f32_e32 v87, v51
	v_exp_f32_e32 v92, v50
	v_cvt_pk_bf16_f32 v50, v61, v62
	v_cvt_pk_bf16_f32 v51, v63, v65
	v_cvt_pk_bf16_f32 v52, v60, v59
	v_cvt_pk_bf16_f32 v53, v58, v86
	v_add_f32_e32 v64, v65, v64
	v_add_f32_e32 v64, v60, v64
	v_mfma_f32_32x32x16_bf16 v[32:47], v[82:85], v[50:53], v[32:47]
	v_add_f32_e32 v64, v59, v64
	v_sub_f32_e32 v54, v56, v15
	v_sub_f32_e32 v14, v14, v15
	v_add_f32_e32 v64, v58, v64
	v_exp_f32_e32 v58, v54
	v_exp_f32_e32 v14, v14
	v_cvt_pk_bf16_f32 v54, v87, v88
	v_mfma_f32_32x32x16_bf16 v[16:31], v[6:9], v[50:53], v[16:31]
	v_cvt_pk_bf16_f32 v55, v89, v90
	v_cvt_pk_bf16_f32 v56, v91, v92
	v_cvt_pk_bf16_f32 v57, v58, v14
	s_add_i32 s60, s60, 1
	s_addk_i32 s65, 0xff80
	s_add_i32 s6, s6, 32
	s_cmpk_lg_i32 s65, 0xfc00
	v_mfma_f32_32x32x16_bf16 v[32:47], v[10:13], v[54:57], v[32:47]
	v_add_f32_e32 v10, v86, v64
	v_add_f32_e32 v10, v87, v10
	v_add_f32_e32 v10, v88, v10
	v_add_f32_e32 v10, v89, v10
	v_add_f32_e32 v10, v90, v10
	v_add_f32_e32 v10, v91, v10
	v_add_f32_e32 v10, v92, v10
	v_mfma_f32_32x32x16_bf16 v[16:31], v[2:5], v[54:57], v[16:31]
	s_setprio 0
	v_add_f32_e32 v6, v58, v10
	v_add_f32_e32 v6, v14, v6
	v_add_f32_e32 v48, v6, v48
	s_cbranch_scc0 .LBB0_355
	v_mov_b32_e32 v106, v0
	s_branch .LBB0_347

; #define LAS __attribute__((address_space(3)))
; #define MFMA32(a, b, c) __builtin_amdgcn_mfma_f32_32x32x16_bf16((a), (b), (c), 0, 0, 0)
; template <int MODE, bool UNI>
; DI void attn_compute(const bf16x8 (&qf)[4], const bf16x8 (&kf)[4], const bf16x8 (&vf)[2][2], int kt, int d00, const float* lut, float ubias, AttnSt& st,
;                      unsigned W, int win, int dmask, bool lane_sel) {
;     const int s0 = kt * 32;
;     const int d0 = d00 - s0;
;     const LAS float* lb = (const LAS float*)lut + ((MODE == 4) ? 16 * (d0 - 23) : (d0 - 23));
;     float bia[16];
;     if (!UNI) {
; #pragma unroll
;         for (int i = 0; i < 16; ++i) { const int ci = 16 * (i >> 3) + (i & 7); bia[i] = (MODE == 4) ? lb[16 * (23 - ci)] : lb[23 - ci]; }
;     }
;     f32x16 sx;
; #pragma unroll
;     for (int i = 0; i < 16; ++i) sx[i] = 0.f;
; #pragma unroll
;     for (int ks = 0; ks < 4; ++ks) sx = MFMA32(kf[ks], qf[ks], sx);
;     asm volatile("s_waitcnt lgkmcnt(0)" ::: "memory");
;     float sv[16]; float mx = NEGF;
; #pragma unroll
;     for (int i = 0; i < 16; ++i) {
;         const int ci = 16 * (i >> 3) + (i & 7);
;         const int dist = d0 - ci;
;         bool v;
;         if (MODE == 0) v = ((W >> ci) & 1u) != 0u;
;         else if (MODE == 1) v = ((unsigned)dist <= (unsigned)win) && ((dist & dmask) == 0);
;         else if (MODE == 2) v = lane_sel;
;         else v = dist >= 0;
;         const float bias = UNI ? ubias : bia[i];
;         float s = fmaf(sx[i], SC2, bias);
;         if (MODE == 0) { const unsigned t = (unsigned)__builtin_amdgcn_sbfe((int)W, ci, 1);
;             s = __uint_as_float((__float_as_uint(s) & t) | (__float_as_uint(NEGF) & ~t)); }
;         else s = v ? s : NEGF;
;         sv[i] = s; mx = fmaxf(mx, s);
;     }
;     mx = fmaxf(mx, __shfl_xor(mx, 32));
;     const float mnew = fmaxf(st.m, mx);
;     const float msafe = (mnew > -1e29f) ? mnew : 0.f;
;     if (__ballot(mnew > st.m) != 0ull) {
;         const float alpha = __builtin_amdgcn_exp2f(st.m - msafe);
;         st.l *= alpha; st.m = mnew;
; #pragma unroll
;         for (int i = 0; i < 16; ++i) { st.o0[i] *= alpha; st.o1[i] *= alpha; }
;     }
.LBB0_361:
	s_waitcnt lgkmcnt(0)
	s_setprio 1
	v_mfma_f32_32x32x16_bf16 v[50:65], v[50:53], v[70:73], 0
	v_cmp_lt_i32_e32 vcc, -1, v14
	v_mfma_f32_32x32x16_bf16 v[50:65], v[90:93], v[66:69], v[50:65]
	v_mfma_f32_32x32x16_bf16 v[50:65], v[94:97], v[78:81], v[50:65]
	ds_read2_b32 v[90:91], v15 offset0:22 offset1:23
	ds_read2_b32 v[92:93], v15 offset0:20 offset1:21
	ds_read2_b32 v[94:95], v15 offset0:18 offset1:19
	ds_read2_b32 v[96:97], v15 offset0:16 offset1:17
	ds_read2_b32 v[104:105], v15 offset0:6 offset1:7
	ds_read2_b32 v[106:107], v15 offset0:4 offset1:5
	ds_read2_b32 v[108:109], v15 offset0:2 offset1:3
	ds_read2_b32 v[110:111], v15 offset1:1
	v_mfma_f32_32x32x16_bf16 v[50:65], v[86:89], v[74:77], v[50:65]
	s_waitcnt lgkmcnt(0)
	s_nop 10
	v_fmamk_f32 v49, v50, 0x3e38aa3b, v91
	v_fmac_f32_e32 v90, 0x3e38aa3b, v51
	v_fmamk_f32 v51, v54, 0x3e38aa3b, v95
	v_cndmask_b32_e32 v54, v239, v49, vcc
	v_cmp_lt_i32_e32 vcc, 0, v14
	v_fmamk_f32 v50, v52, 0x3e38aa3b, v93
	v_fmac_f32_e32 v94, 0x3e38aa3b, v55
	v_cndmask_b32_e32 v55, v239, v90, vcc
	v_cmp_lt_i32_e32 vcc, 1, v14
	v_fmac_f32_e32 v92, 0x3e38aa3b, v53
	v_fmamk_f32 v53, v56, 0x3e38aa3b, v97
	v_cndmask_b32_e32 v56, v239, v50, vcc
	v_cmp_lt_i32_e32 vcc, 2, v14
	v_fmac_f32_e32 v96, 0x3e38aa3b, v57
	v_fmac_f32_e32 v104, 0x3e38aa3b, v59
	v_cndmask_b32_e32 v50, v239, v92, vcc
	v_cmp_lt_i32_e32 vcc, 3, v14
	v_max3_f32 v49, v54, s30, v55
	v_max3_f32 v49, v49, v56, v50
	v_cndmask_b32_e32 v51, v239, v51, vcc
	v_cmp_lt_i32_e32 vcc, 4, v14
	v_fmac_f32_e32 v106, 0x3e38aa3b, v61
	v_fmac_f32_e32 v108, 0x3e38aa3b, v63
	v_cndmask_b32_e32 v52, v239, v94, vcc
	v_cmp_lt_i32_e32 vcc, 5, v14
	v_max3_f32 v49, v49, v51, v52
	v_fmac_f32_e32 v110, 0x3e38aa3b, v65
	v_cndmask_b32_e32 v86, v239, v53, vcc
	v_cmp_lt_i32_e32 vcc, 6, v14
	v_fmamk_f32 v53, v58, 0x3e38aa3b, v105
	s_nop 0
	v_cndmask_b32_e32 v87, v239, v96, vcc
	v_cmp_lt_i32_e32 vcc, 15, v14
	v_max3_f32 v49, v49, v86, v87
	s_nop 0
	v_cndmask_b32_e32 v58, v239, v53, vcc
	v_cmp_lt_i32_e32 vcc, 16, v14
	v_fmamk_f32 v53, v60, 0x3e38aa3b, v107
	s_nop 0
	v_cndmask_b32_e32 v59, v239, v104, vcc
	v_cmp_lt_i32_e32 vcc, 17, v14
	v_max3_f32 v49, v49, v58, v59
	s_nop 0
	v_cndmask_b32_e32 v60, v239, v53, vcc
	v_cmp_lt_i32_e32 vcc, 18, v14
	v_fmamk_f32 v53, v62, 0x3e38aa3b, v109
	s_nop 0
	v_cndmask_b32_e32 v61, v239, v106, vcc
	v_cmp_lt_i32_e32 vcc, 19, v14
	v_max3_f32 v49, v49, v60, v61
	s_nop 0
	v_cndmask_b32_e32 v62, v239, v53, vcc
	v_cmp_lt_i32_e32 vcc, 20, v14
	v_fmamk_f32 v53, v64, 0x3e38aa3b, v111
	s_nop 0
	v_cndmask_b32_e32 v63, v239, v108, vcc
	v_cmp_lt_i32_e32 vcc, 21, v14
	v_max3_f32 v49, v49, v62, v63
	s_nop 0
	v_cndmask_b32_e32 v64, v239, v53, vcc
	v_cmp_lt_i32_e32 vcc, 22, v14
	s_nop 1
	v_cndmask_b32_e32 v53, v239, v110, vcc
	v_max3_f32 v49, v49, v64, v53
	v_mov_b32_e32 v57, v49
	s_nop 1
	v_permlane32_swap_b32_e32 v57, v49
	s_waitcnt lgkmcnt(0)
	v_max3_f32 v49, v0, v49, v57
	v_cmp_lt_f32_e32 vcc, s12, v49
	s_nop 1
	v_cndmask_b32_e32 v57, 0, v49, vcc
	v_cmp_gt_f32_e32 vcc, v49, v0
	s_cbranch_vccz .LBB0_363
	v_sub_f32_e32 v0, v0, v57
	v_exp_f32_e32 v0, v0
	s_nop 0
	v_mul_f32_e32 v48, v48, v0
	v_pk_mul_f32 v[46:47], v[46:47], v[0:1] op_sel_hi:[1,0]
	v_pk_mul_f32 v[44:45], v[44:45], v[0:1] op_sel_hi:[1,0]
	v_pk_mul_f32 v[42:43], v[42:43], v[0:1] op_sel_hi:[1,0]
	v_pk_mul_f32 v[40:41], v[40:41], v[0:1] op_sel_hi:[1,0]
	v_pk_mul_f32 v[38:39], v[38:39], v[0:1] op_sel_hi:[1,0]
	v_pk_mul_f32 v[36:37], v[36:37], v[0:1] op_sel_hi:[1,0]
	v_pk_mul_f32 v[34:35], v[34:35], v[0:1] op_sel_hi:[1,0]
	v_pk_mul_f32 v[32:33], v[32:33], v[0:1] op_sel_hi:[1,0]
	v_pk_mul_f32 v[30:31], v[30:31], v[0:1] op_sel_hi:[1,0]
	v_pk_mul_f32 v[28:29], v[28:29], v[0:1] op_sel_hi:[1,0]
	v_pk_mul_f32 v[26:27], v[26:27], v[0:1] op_sel_hi:[1,0]
	v_pk_mul_f32 v[24:25], v[24:25], v[0:1] op_sel_hi:[1,0]
	v_pk_mul_f32 v[22:23], v[22:23], v[0:1] op_sel_hi:[1,0]
	v_pk_mul_f32 v[20:21], v[20:21], v[0:1] op_sel_hi:[1,0]
	v_pk_mul_f32 v[18:19], v[18:19], v[0:1] op_sel_hi:[1,0]
	v_pk_mul_f32 v[16:17], v[16:17], v[0:1] op_sel_hi:[1,0]
	s_branch .LBB0_364

; #define LAS __attribute__((address_space(3)))
; template <int MODE, bool UNI>
; DI void attn_compute(const bf16x8 (&qf)[4], const bf16x8 (&kf)[4], const bf16x8 (&vf)[2][2], int kt, int d00, const float* lut, float ubias, AttnSt& st,
;                      unsigned W, int win, int dmask, bool lane_sel) {
;     ...
;     float ps = 0.f; float p[16];
; #pragma unroll
;     for (int i = 0; i < 16; ++i) { const float e = __builtin_amdgcn_exp2f(sv[i] - msafe); p[i] = e; ps += e; }
;     st.l += ps;
;     u32x4 w0, w1;
;     w0.x = pk2(p[0], p[1]); w0.y = pk2(p[2], p[3]); w0.z = pk2(p[4], p[5]); w0.w = pk2(p[6], p[7]);
;     w1.x = pk2(p[8], p[9]); w1.y = pk2(p[10], p[11]); w1.z = pk2(p[12], p[13]); w1.w = pk2(p[14], p[15]);
;     const bf16x8 pf0 = __builtin_bit_cast(bf16x8, w0), pf1 = __builtin_bit_cast(bf16x8, w1);
;     st.o0 = MFMA32(vf[0][0], pf0, st.o0); st.o0 = MFMA32(vf[0][1], pf1, st.o0);
;     st.o1 = MFMA32(vf[1][0], pf0, st.o1); st.o1 = MFMA32(vf[1][1], pf1, st.o1);
; template <int MODE>
; DI void attn_range(const AttnCtx& c, const bf16x8 (&qf)[4], int lo, int hi, int t0, int d00, AttnSt& st, const unsigned* maskrow, int h8, int win, int dmask, bool lane_sel) {
;     ...
;     for (int kt = lo; kt <= hi; ++kt) {
;         asm volatile("s_waitcnt vmcnt(0)" ::: "memory");
;         bf16x8 kf[4], vf[2][2];
; #pragma unroll
;         for (int ks = 0; ks < 4; ++ks) kf[ks] = *(const LAS bf16x8*)(c.wl + c.kfo[ks]);
; #pragma unroll
;         for (int mt = 0; mt < 2; ++mt)
; #pragma unroll
;             for (int s = 0; s < 2; ++s) vf[mt][s] = *(const LAS bf16x8*)(c.wl + 4096 + c.vfo[mt][s]);
;         const unsigned W = Wn >> h8;
;         const int dlo = t0 - kt * 32 - 31;
;         float ub = 0.f; bool uni = false;
;         if (dlo >= 182) { const unsigned ua = __builtin_amdgcn_readfirstlane(__float_as_uint(c.lut[dlo])), ue = __builtin_amdgcn_readfirstlane(__float_as_uint(c.lut[dlo + 62])); uni = (ua == ue); ub = __uint_as_float(ua); }
;         asm volatile("s_waitcnt lgkmcnt(0)" ::: "memory");
;         if (kt < hi) { attn_dma(c, kt + 1); if (MODE == 0) Wn = maskrow[kt + 1]; }
;         if (MODE == 1 && dmask != 0) attn_compute_sp4(qf, kf, vf, kt, d00, c.lut, st, win, dmask);
;         else attn_compute<MODE, false>(qf, kf, vf, kt, d00, c.lut, 0.f, st, W, win, dmask, lane_sel);
;     }
.LBB0_364:
	v_sub_f32_e32 v50, v50, v57
	v_exp_f32_e32 v65, v50
	v_sub_f32_e32 v50, v51, v57
	v_exp_f32_e32 v88, v50
	v_sub_f32_e32 v50, v52, v57
	v_exp_f32_e32 v89, v50
	v_sub_f32_e32 v50, v86, v57
	v_sub_f32_e32 v0, v54, v57
	v_sub_f32_e32 v54, v55, v57
	v_sub_f32_e32 v55, v56, v57
	v_exp_f32_e32 v86, v50
	v_sub_f32_e32 v50, v87, v57
	v_exp_f32_e32 v0, v0
	v_exp_f32_e32 v54, v54
	v_exp_f32_e32 v55, v55
	v_exp_f32_e32 v87, v50
	v_sub_f32_e32 v50, v58, v57
	v_exp_f32_e32 v90, v50
	v_sub_f32_e32 v50, v59, v57
	v_exp_f32_e32 v91, v50
	v_sub_f32_e32 v50, v60, v57
	v_exp_f32_e32 v92, v50
	v_sub_f32_e32 v50, v61, v57
	v_exp_f32_e32 v93, v50
	v_sub_f32_e32 v50, v62, v57
	v_cvt_pk_bf16_f32 v58, v0, v54
	v_cvt_pk_bf16_f32 v59, v55, v65
	v_cvt_pk_bf16_f32 v60, v88, v89
	v_cvt_pk_bf16_f32 v61, v86, v87
	v_exp_f32_e32 v62, v50
	v_sub_f32_e32 v50, v63, v57
	v_mfma_f32_32x32x16_bf16 v[32:47], v[82:85], v[58:61], v[32:47]
	v_exp_f32_e32 v63, v50
	v_sub_f32_e32 v50, v64, v57
	v_add_f32_e32 v56, 0, v0
	v_exp_f32_e32 v0, v50
	v_sub_f32_e32 v50, v53, v57
	v_add_f32_e32 v56, v54, v56
	v_exp_f32_e32 v54, v50
	v_mfma_f32_32x32x16_bf16 v[16:31], v[6:9], v[58:61], v[16:31]
	v_add_f32_e32 v56, v55, v56
	v_cvt_pk_bf16_f32 v50, v90, v91
	v_cvt_pk_bf16_f32 v51, v92, v93
	v_cvt_pk_bf16_f32 v52, v62, v63
	v_cvt_pk_bf16_f32 v53, v0, v54
	s_add_i32 s2, s2, 1
	s_add_i32 s0, s0, 32
	v_mfma_f32_32x32x16_bf16 v[32:47], v[10:13], v[50:53], v[32:47]
	v_add_f32_e32 v10, v65, v56
	v_add_f32_e32 v10, v88, v10
	v_add_f32_e32 v10, v89, v10
	v_add_f32_e32 v10, v86, v10
	v_add_f32_e32 v10, v87, v10
	v_add_f32_e32 v10, v90, v10
	v_add_f32_e32 v10, v91, v10
	v_mfma_f32_32x32x16_bf16 v[16:31], v[2:5], v[50:53], v[16:31]
	s_setprio 0
	v_add_f32_e32 v6, v92, v10
	v_add_f32_e32 v6, v93, v6
	v_add_f32_e32 v6, v62, v6
	v_add_f32_e32 v6, v63, v6
	v_add_f32_e32 v0, v0, v6
	v_add_f32_e32 v0, v54, v0
	v_add_f32_e32 v48, v0, v48
	v_add_u32_e32 v15, 0xffffff80, v15
	v_subrev_u32_e32 v14, 32, v14
	s_and_b64 vcc, exec, s[6:7]
	s_cbranch_vccnz .LBB0_268
	v_mov_b32_e32 v0, v49
	s_branch .LBB0_359
